# S5 pass2 output projection: the four state-fragment LDS reads issued together with counted lgkmcnt waits per MFMA
# speedup vs baseline: 1.0020x; 1.0020x over previous
.LBB0_1787:
	s_or_b64 exec, exec, s[0:1]
	s_movk_i32 s1, 0x3200
	v_mul_lo_u32 v72, v82, s1
	v_add_u32_e32 v81, 0, v72
	s_waitcnt vmcnt(0) lgkmcnt(0)
	v_mov_b32_e32 v158, 0x5040100
	v_mov_b32_e32 v159, 0x7060302
	v_perm_b32 v24, v142, v140, v158
	v_perm_b32 v25, v142, v140, v159
	v_perm_b32 v26, v143, v141, v158
	v_perm_b32 v27, v143, v141, v159
	v_perm_b32 v20, v146, v144, v158
	v_perm_b32 v21, v146, v144, v159
	v_perm_b32 v22, v147, v145, v158
	v_perm_b32 v23, v147, v145, v159
	v_perm_b32 v16, v150, v148, v158
	v_perm_b32 v17, v150, v148, v159
	v_perm_b32 v18, v151, v149, v158
	v_perm_b32 v19, v151, v149, v159
	v_perm_b32 v12, v154, v152, v158
	v_perm_b32 v13, v154, v152, v159
	v_perm_b32 v14, v155, v153, v158
	v_perm_b32 v15, v155, v153, v159
	v_mfma_f32_16x16x32_bf16 v[84:87], v[0:3], v[32:35], 0
	v_mul_u32_u24_e32 v72, 0x210, v83
	v_lshlrev_b32_e32 v73, 2, v79
	v_lshlrev_b32_e32 v72, 2, v72
	v_mfma_f32_16x16x32_bf16 v[96:99], v[0:3], v[28:31], 0
	v_add3_u32 v73, v81, v73, v72
	v_add_u32_e32 v74, 0x400, v73
	s_nop 5
	ds_write2_b32 v73, v84, v96 offset1:16
	ds_write2_b32 v73, v85, v97 offset0:132 offset1:148
	ds_write2_b32 v74, v86, v98 offset0:8 offset1:24
	ds_write2_b32 v74, v87, v99 offset0:140 offset1:156
	v_mfma_f32_16x16x32_bf16 v[82:85], v[0:3], v[40:43], 0
	v_lshl_add_u32 v75, v78, 2, v81
	s_cmp_gt_i32 s9, 3
	s_cselect_b32 s0, 0x87, 3
	v_mfma_f32_16x16x32_bf16 v[86:89], v[0:3], v[36:39], 0
	s_nop 7
	ds_write2_b32 v73, v82, v86 offset0:32 offset1:48
	ds_write2_b32 v73, v83, v87 offset0:164 offset1:180
	ds_write2_b32 v74, v84, v88 offset0:40 offset1:56
	ds_write2_b32 v74, v85, v89 offset0:172 offset1:188
	v_mfma_f32_16x16x32_bf16 v[82:85], v[0:3], v[48:51], 0
	s_sub_i32 s0, s0, s9
	v_mul_u32_u24_e32 v94, 0x110, v79
	v_add_u32_e32 v79, 64, v75
	v_mfma_f32_16x16x32_bf16 v[86:89], v[0:3], v[44:47], 0
	s_nop 7
	ds_write2_b32 v73, v82, v86 offset0:64 offset1:80
	ds_write2_b32 v73, v83, v87 offset0:196 offset1:212
	ds_write2_b32 v74, v84, v88 offset0:72 offset1:88
	ds_write2_b32 v74, v85, v89 offset0:204 offset1:220
	v_mfma_f32_16x16x32_bf16 v[82:85], v[0:3], v[56:59], 0
	v_add_u32_e32 v86, 0x90, v75
	v_add_u32_e32 v87, 0xa0, v75
	v_add_u32_e32 v88, 0xb0, v75
	v_mfma_f32_16x16x32_bf16 v[0:3], v[0:3], v[52:55], 0
	s_nop 7
	ds_write2_b32 v73, v82, v0 offset0:96 offset1:112
	ds_write2_b32 v73, v83, v1 offset0:228 offset1:244
	ds_write2_b32 v74, v84, v2 offset0:104 offset1:120
	ds_write2_b32 v74, v85, v3 offset0:236 offset1:252
	v_lshlrev_b32_e32 v0, 1, v78
	s_waitcnt vmcnt(0) lgkmcnt(0)
	v_sub_u32_e32 v72, v75, v0
	ds_read2st64_b32 v[0:1], v75 offset1:1
	ds_read2_b32 v[140:141], v75 offset0:132 offset1:196
	v_add_u32_e32 v142, 32, v75
	ds_read2st64_b32 v[144:145], v142 offset0:4 offset1:5
	v_add_u32_e32 v143, 48, v75
	ds_read2st64_b32 v[146:147], v143 offset0:6 offset1:7
	ds_read2st64_b32 v[148:149], v79 offset0:8 offset1:9
	v_add_u32_e32 v150, 0x50, v75
	ds_read2st64_b32 v[152:153], v150 offset0:10 offset1:11
	v_add_u32_e32 v151, 0x60, v75
	ds_read2st64_b32 v[154:155], v151 offset0:12 offset1:13
	v_add_u32_e32 v156, 0x70, v75
	ds_read2st64_b32 v[158:159], v156 offset0:14 offset1:15
	v_add_u32_e32 v157, 0x80, v75
	ds_read2st64_b32 v[160:161], v157 offset0:16 offset1:17
	ds_read2st64_b32 v[162:163], v86 offset0:18 offset1:19
	ds_read2st64_b32 v[164:165], v87 offset0:20 offset1:21
	ds_read2st64_b32 v[166:167], v88 offset0:22 offset1:23
	v_add_u32_e32 v168, 0xc0, v75
	ds_read2st64_b32 v[170:171], v168 offset0:24 offset1:25
	v_add_u32_e32 v169, 0xd0, v75
	ds_read2st64_b32 v[172:173], v169 offset0:26 offset1:27
	v_add_u32_e32 v174, 0xe0, v75
	ds_read2st64_b32 v[176:177], v174 offset0:28 offset1:29
	v_add_u32_e32 v175, 0xf0, v75
	ds_read2st64_b32 v[178:179], v175 offset0:30 offset1:31
	v_mov_b32_e32 v186, v70
	v_mov_b32_e32 v187, v71
	v_add_u32_e32 v78, 48, v75
	v_add_u32_e32 v82, 0x50, v75
	s_waitcnt lgkmcnt(0)
	v_pk_fma_f32 v[184:185], v[66:67], v[186:187], v[0:1] op_sel:[1,1,0] op_sel_hi:[1,0,1] neg_lo:[1,0,0]
	v_pk_fma_f32 v[188:189], v[66:67], v[186:187], v[184:185] op_sel_hi:[0,1,1]
	v_cvt_pk_bf16_f32 v190, v188, v189
	v_and_b32_e32 v191, 63, v207
	v_lshl_add_u32 v191, v191, 1, v72
	ds_write_b32 v191, v190 offset:8448
	v_add_u32_e32 v71, 32, v75
	v_add_u32_e32 v83, 0x60, v75
	v_pk_fma_f32 v[184:185], v[66:67], v[188:189], v[140:141] op_sel:[1,1,0] op_sel_hi:[1,0,1] neg_lo:[1,0,0]
	v_pk_fma_f32 v[186:187], v[66:67], v[188:189], v[184:185] op_sel_hi:[0,1,1]
	v_cvt_pk_bf16_f32 v190, v186, v187
	ds_write_b32 v191, v190 offset:8720
	v_add_u32_e32 v84, 0x70, v75
	v_add_u32_e32 v85, 0x80, v75
	v_pk_fma_f32 v[184:185], v[66:67], v[186:187], v[144:145] op_sel:[1,1,0] op_sel_hi:[1,0,1] neg_lo:[1,0,0]
	v_pk_fma_f32 v[188:189], v[66:67], v[186:187], v[184:185] op_sel_hi:[0,1,1]
	v_cvt_pk_bf16_f32 v190, v188, v189
	ds_write_b32 v191, v190 offset:8992
	v_add_u32_e32 v89, 0xc0, v75
	v_add_u32_e32 v91, 0xd0, v75
	v_pk_fma_f32 v[184:185], v[66:67], v[188:189], v[146:147] op_sel:[1,1,0] op_sel_hi:[1,0,1] neg_lo:[1,0,0]
	v_pk_fma_f32 v[186:187], v[66:67], v[188:189], v[184:185] op_sel_hi:[0,1,1]
	v_cvt_pk_bf16_f32 v190, v186, v187
	ds_write_b32 v191, v190 offset:9264
	v_add_u32_e32 v92, 0xe0, v75
	v_add_u32_e32 v93, 0xf0, v75
	v_pk_fma_f32 v[184:185], v[66:67], v[186:187], v[148:149] op_sel:[1,1,0] op_sel_hi:[1,0,1] neg_lo:[1,0,0]
	v_pk_fma_f32 v[188:189], v[66:67], v[186:187], v[184:185] op_sel_hi:[0,1,1]
	v_cvt_pk_bf16_f32 v190, v188, v189
	ds_write_b32 v191, v190 offset:9536
	v_mfma_f32_16x16x32_bf16 v[98:101], v[4:7], v[28:31], 0
	s_or_b32 s1, s2, 0x84
	v_pk_fma_f32 v[184:185], v[66:67], v[188:189], v[152:153] op_sel:[1,1,0] op_sel_hi:[1,0,1] neg_lo:[1,0,0]
	v_pk_fma_f32 v[186:187], v[66:67], v[188:189], v[184:185] op_sel_hi:[0,1,1]
	v_cvt_pk_bf16_f32 v190, v186, v187
	ds_write_b32 v191, v190 offset:9808
	s_ashr_i32 s2, s0, 31
	v_pk_fma_f32 v[184:185], v[66:67], v[186:187], v[154:155] op_sel:[1,1,0] op_sel_hi:[1,0,1] neg_lo:[1,0,0]
	v_pk_fma_f32 v[188:189], v[66:67], v[186:187], v[184:185] op_sel_hi:[0,1,1]
	v_cvt_pk_bf16_f32 v190, v188, v189
	ds_write_b32 v191, v190 offset:10080
	v_pk_fma_f32 v[184:185], v[66:67], v[188:189], v[158:159] op_sel:[1,1,0] op_sel_hi:[1,0,1] neg_lo:[1,0,0]
	v_pk_fma_f32 v[186:187], v[66:67], v[188:189], v[184:185] op_sel_hi:[0,1,1]
	v_cvt_pk_bf16_f32 v190, v186, v187
	ds_write_b32 v191, v190 offset:10352
	v_pk_fma_f32 v[184:185], v[66:67], v[186:187], v[160:161] op_sel:[1,1,0] op_sel_hi:[1,0,1] neg_lo:[1,0,0]
	v_pk_fma_f32 v[188:189], v[66:67], v[186:187], v[184:185] op_sel_hi:[0,1,1]
	v_cvt_pk_bf16_f32 v190, v188, v189
	ds_write_b32 v191, v190 offset:10624
	v_pk_fma_f32 v[184:185], v[66:67], v[188:189], v[162:163] op_sel:[1,1,0] op_sel_hi:[1,0,1] neg_lo:[1,0,0]
	v_pk_fma_f32 v[186:187], v[66:67], v[188:189], v[184:185] op_sel_hi:[0,1,1]
	v_cvt_pk_bf16_f32 v190, v186, v187
	ds_write_b32 v191, v190 offset:10896
	v_pk_fma_f32 v[184:185], v[66:67], v[186:187], v[164:165] op_sel:[1,1,0] op_sel_hi:[1,0,1] neg_lo:[1,0,0]
	v_pk_fma_f32 v[188:189], v[66:67], v[186:187], v[184:185] op_sel_hi:[0,1,1]
	v_cvt_pk_bf16_f32 v190, v188, v189
	ds_write_b32 v191, v190 offset:11168
	v_pk_fma_f32 v[184:185], v[66:67], v[188:189], v[166:167] op_sel:[1,1,0] op_sel_hi:[1,0,1] neg_lo:[1,0,0]
	v_pk_fma_f32 v[186:187], v[66:67], v[188:189], v[184:185] op_sel_hi:[0,1,1]
	v_cvt_pk_bf16_f32 v190, v186, v187
	ds_write_b32 v191, v190 offset:11440
	v_pk_fma_f32 v[184:185], v[66:67], v[186:187], v[170:171] op_sel:[1,1,0] op_sel_hi:[1,0,1] neg_lo:[1,0,0]
	v_pk_fma_f32 v[188:189], v[66:67], v[186:187], v[184:185] op_sel_hi:[0,1,1]
	v_cvt_pk_bf16_f32 v190, v188, v189
	ds_write_b32 v191, v190 offset:11712
	v_pk_fma_f32 v[184:185], v[66:67], v[188:189], v[172:173] op_sel:[1,1,0] op_sel_hi:[1,0,1] neg_lo:[1,0,0]
	v_pk_fma_f32 v[186:187], v[66:67], v[188:189], v[184:185] op_sel_hi:[0,1,1]
	v_cvt_pk_bf16_f32 v190, v186, v187
	ds_write_b32 v191, v190 offset:11984
	v_pk_fma_f32 v[184:185], v[66:67], v[186:187], v[176:177] op_sel:[1,1,0] op_sel_hi:[1,0,1] neg_lo:[1,0,0]
	v_pk_fma_f32 v[188:189], v[66:67], v[186:187], v[184:185] op_sel_hi:[0,1,1]
	v_cvt_pk_bf16_f32 v190, v188, v189
	ds_write_b32 v191, v190 offset:12256
	v_pk_fma_f32 v[184:185], v[66:67], v[188:189], v[178:179] op_sel:[1,1,0] op_sel_hi:[1,0,1] neg_lo:[1,0,0]
	v_pk_fma_f32 v[186:187], v[66:67], v[188:189], v[184:185] op_sel_hi:[0,1,1]
	v_mov_b32_e32 v102, v186
	v_mov_b32_e32 v103, v187
	v_cvt_pk_bf16_f32 v190, v186, v187
	ds_write_b32 v191, v190 offset:12528
	v_add3_u32 v70, v81, v128, v94
	s_waitcnt vmcnt(0) lgkmcnt(0)
	ds_read_b128 v[0:3], v70 offset:8448
	ds_read_b128 v[94:97], v70 offset:8512
	ds_read_b128 v[140:143], v70 offset:8576
	ds_read_b128 v[144:147], v70 offset:8640
	s_waitcnt lgkmcnt(3)
	v_mfma_f32_16x16x32_bf16 v[0:3], v[0:3], v[24:27], 0
	s_waitcnt lgkmcnt(2)
	v_mfma_f32_16x16x32_bf16 v[0:3], v[94:97], v[20:23], v[0:3]
	s_waitcnt lgkmcnt(1)
	v_mfma_f32_16x16x32_bf16 v[0:3], v[140:143], v[16:19], v[0:3]
	s_waitcnt lgkmcnt(0)
	v_mfma_f32_16x16x32_bf16 v[0:3], v[144:147], v[12:15], v[0:3]
	v_mfma_f32_16x16x32_bf16 v[94:97], v[4:7], v[32:35], 0
	s_nop 7
	ds_write2_b32 v73, v94, v98 offset1:16
	ds_write2_b32 v73, v95, v99 offset0:132 offset1:148
	ds_write2_b32 v74, v96, v100 offset0:8 offset1:24
	ds_write2_b32 v74, v97, v101 offset0:140 offset1:156
	v_mfma_f32_16x16x32_bf16 v[94:97], v[4:7], v[40:43], 0
	v_mfma_f32_16x16x32_bf16 v[98:101], v[4:7], v[36:39], 0
	s_nop 7
	ds_write2_b32 v73, v94, v98 offset0:32 offset1:48
	ds_write2_b32 v73, v95, v99 offset0:164 offset1:180
	ds_write2_b32 v74, v96, v100 offset0:40 offset1:56
	ds_write2_b32 v74, v97, v101 offset0:172 offset1:188
	v_mfma_f32_16x16x32_bf16 v[94:97], v[4:7], v[48:51], 0
	v_mfma_f32_16x16x32_bf16 v[98:101], v[4:7], v[44:47], 0
	s_nop 7
	ds_write2_b32 v73, v94, v98 offset0:64 offset1:80
	ds_write2_b32 v73, v95, v99 offset0:196 offset1:212
	ds_write2_b32 v74, v96, v100 offset0:72 offset1:88
	ds_write2_b32 v74, v97, v101 offset0:204 offset1:220
	v_mfma_f32_16x16x32_bf16 v[94:97], v[4:7], v[56:59], 0
	v_mfma_f32_16x16x32_bf16 v[4:7], v[4:7], v[52:55], 0
	s_nop 7
	ds_write2_b32 v73, v94, v4 offset0:96 offset1:112
	ds_write2_b32 v73, v95, v5 offset0:228 offset1:244
	ds_write2_b32 v74, v96, v6 offset0:104 offset1:120
	ds_write2_b32 v74, v97, v7 offset0:236 offset1:252
	s_waitcnt vmcnt(0) lgkmcnt(0)
	ds_read2st64_b32 v[4:5], v75 offset1:1
	ds_read2_b32 v[140:141], v75 offset0:132 offset1:196
	ds_read2st64_b32 v[142:143], v71 offset0:4 offset1:5
	ds_read2st64_b32 v[144:145], v78 offset0:6 offset1:7
	ds_read2st64_b32 v[146:147], v79 offset0:8 offset1:9
	ds_read2st64_b32 v[148:149], v82 offset0:10 offset1:11
	ds_read2st64_b32 v[150:151], v83 offset0:12 offset1:13
	ds_read2st64_b32 v[152:153], v84 offset0:14 offset1:15
	ds_read2st64_b32 v[154:155], v85 offset0:16 offset1:17
	ds_read2st64_b32 v[156:157], v86 offset0:18 offset1:19
	ds_read2st64_b32 v[158:159], v87 offset0:20 offset1:21
	ds_read2st64_b32 v[160:161], v88 offset0:22 offset1:23
	ds_read2st64_b32 v[162:163], v89 offset0:24 offset1:25
	ds_read2st64_b32 v[164:165], v91 offset0:26 offset1:27
	ds_read2st64_b32 v[166:167], v92 offset0:28 offset1:29
	ds_read2st64_b32 v[168:169], v93 offset0:30 offset1:31
	v_mov_b32_e32 v186, v102
	v_mov_b32_e32 v187, v103
	v_mfma_f32_16x16x32_bf16 v[98:101], v[8:11], v[28:31], 0
	s_waitcnt lgkmcnt(0)
	v_pk_fma_f32 v[184:185], v[66:67], v[186:187], v[4:5] op_sel:[1,1,0] op_sel_hi:[1,0,1] neg_lo:[1,0,0]
	v_pk_fma_f32 v[188:189], v[66:67], v[186:187], v[184:185] op_sel_hi:[0,1,1]
	v_cvt_pk_bf16_f32 v190, v188, v189
	v_and_b32_e32 v191, 63, v207
	v_lshl_add_u32 v191, v191, 1, v72
	ds_write_b32 v191, v190 offset:8448
	v_mfma_f32_16x16x32_bf16 v[28:31], v[60:63], v[28:31], 0
	v_pk_fma_f32 v[184:185], v[66:67], v[188:189], v[140:141] op_sel:[1,1,0] op_sel_hi:[1,0,1] neg_lo:[1,0,0]
	v_pk_fma_f32 v[186:187], v[66:67], v[188:189], v[184:185] op_sel_hi:[0,1,1]
	v_cvt_pk_bf16_f32 v190, v186, v187
	ds_write_b32 v191, v190 offset:8720
	v_pk_fma_f32 v[184:185], v[66:67], v[186:187], v[142:143] op_sel:[1,1,0] op_sel_hi:[1,0,1] neg_lo:[1,0,0]
	v_pk_fma_f32 v[188:189], v[66:67], v[186:187], v[184:185] op_sel_hi:[0,1,1]
	v_cvt_pk_bf16_f32 v190, v188, v189
	ds_write_b32 v191, v190 offset:8992
	v_pk_fma_f32 v[184:185], v[66:67], v[188:189], v[144:145] op_sel:[1,1,0] op_sel_hi:[1,0,1] neg_lo:[1,0,0]
	v_pk_fma_f32 v[186:187], v[66:67], v[188:189], v[184:185] op_sel_hi:[0,1,1]
	v_cvt_pk_bf16_f32 v190, v186, v187
	ds_write_b32 v191, v190 offset:9264
	v_pk_fma_f32 v[184:185], v[66:67], v[186:187], v[146:147] op_sel:[1,1,0] op_sel_hi:[1,0,1] neg_lo:[1,0,0]
	v_pk_fma_f32 v[188:189], v[66:67], v[186:187], v[184:185] op_sel_hi:[0,1,1]
	v_cvt_pk_bf16_f32 v190, v188, v189
	ds_write_b32 v191, v190 offset:9536
	v_pk_fma_f32 v[184:185], v[66:67], v[188:189], v[148:149] op_sel:[1,1,0] op_sel_hi:[1,0,1] neg_lo:[1,0,0]
	v_pk_fma_f32 v[186:187], v[66:67], v[188:189], v[184:185] op_sel_hi:[0,1,1]
	v_cvt_pk_bf16_f32 v190, v186, v187
	ds_write_b32 v191, v190 offset:9808
	v_pk_fma_f32 v[184:185], v[66:67], v[186:187], v[150:151] op_sel:[1,1,0] op_sel_hi:[1,0,1] neg_lo:[1,0,0]
	v_pk_fma_f32 v[188:189], v[66:67], v[186:187], v[184:185] op_sel_hi:[0,1,1]
	v_cvt_pk_bf16_f32 v190, v188, v189
	ds_write_b32 v191, v190 offset:10080
	v_pk_fma_f32 v[184:185], v[66:67], v[188:189], v[152:153] op_sel:[1,1,0] op_sel_hi:[1,0,1] neg_lo:[1,0,0]
	v_pk_fma_f32 v[186:187], v[66:67], v[188:189], v[184:185] op_sel_hi:[0,1,1]
	v_cvt_pk_bf16_f32 v190, v186, v187
	ds_write_b32 v191, v190 offset:10352
	v_pk_fma_f32 v[184:185], v[66:67], v[186:187], v[154:155] op_sel:[1,1,0] op_sel_hi:[1,0,1] neg_lo:[1,0,0]
	v_pk_fma_f32 v[188:189], v[66:67], v[186:187], v[184:185] op_sel_hi:[0,1,1]
	v_cvt_pk_bf16_f32 v190, v188, v189
	ds_write_b32 v191, v190 offset:10624
	v_pk_fma_f32 v[184:185], v[66:67], v[188:189], v[156:157] op_sel:[1,1,0] op_sel_hi:[1,0,1] neg_lo:[1,0,0]
	v_pk_fma_f32 v[186:187], v[66:67], v[188:189], v[184:185] op_sel_hi:[0,1,1]
	v_cvt_pk_bf16_f32 v190, v186, v187
	ds_write_b32 v191, v190 offset:10896
	v_pk_fma_f32 v[184:185], v[66:67], v[186:187], v[158:159] op_sel:[1,1,0] op_sel_hi:[1,0,1] neg_lo:[1,0,0]
	v_pk_fma_f32 v[188:189], v[66:67], v[186:187], v[184:185] op_sel_hi:[0,1,1]
	v_cvt_pk_bf16_f32 v190, v188, v189
	ds_write_b32 v191, v190 offset:11168
	v_pk_fma_f32 v[184:185], v[66:67], v[188:189], v[160:161] op_sel:[1,1,0] op_sel_hi:[1,0,1] neg_lo:[1,0,0]
	v_pk_fma_f32 v[186:187], v[66:67], v[188:189], v[184:185] op_sel_hi:[0,1,1]
	v_cvt_pk_bf16_f32 v190, v186, v187
	ds_write_b32 v191, v190 offset:11440
	v_pk_fma_f32 v[184:185], v[66:67], v[186:187], v[162:163] op_sel:[1,1,0] op_sel_hi:[1,0,1] neg_lo:[1,0,0]
	v_pk_fma_f32 v[188:189], v[66:67], v[186:187], v[184:185] op_sel_hi:[0,1,1]
	v_cvt_pk_bf16_f32 v190, v188, v189
	ds_write_b32 v191, v190 offset:11712
	v_pk_fma_f32 v[184:185], v[66:67], v[188:189], v[164:165] op_sel:[1,1,0] op_sel_hi:[1,0,1] neg_lo:[1,0,0]
	v_pk_fma_f32 v[186:187], v[66:67], v[188:189], v[184:185] op_sel_hi:[0,1,1]
	v_cvt_pk_bf16_f32 v190, v186, v187
	ds_write_b32 v191, v190 offset:11984
	v_pk_fma_f32 v[184:185], v[66:67], v[186:187], v[166:167] op_sel:[1,1,0] op_sel_hi:[1,0,1] neg_lo:[1,0,0]
	v_pk_fma_f32 v[188:189], v[66:67], v[186:187], v[184:185] op_sel_hi:[0,1,1]
	v_cvt_pk_bf16_f32 v190, v188, v189
	ds_write_b32 v191, v190 offset:12256
	v_pk_fma_f32 v[184:185], v[66:67], v[188:189], v[168:169] op_sel:[1,1,0] op_sel_hi:[1,0,1] neg_lo:[1,0,0]
	v_pk_fma_f32 v[186:187], v[66:67], v[188:189], v[184:185] op_sel_hi:[0,1,1]
	v_mov_b32_e32 v102, v186
	v_mov_b32_e32 v103, v187
	v_cvt_pk_bf16_f32 v190, v186, v187
	ds_write_b32 v191, v190 offset:12528
	s_waitcnt vmcnt(0) lgkmcnt(0)
	ds_read_b128 v[4:7], v70 offset:8448
	ds_read_b128 v[94:97], v70 offset:8512
	ds_read_b128 v[140:143], v70 offset:8576
	ds_read_b128 v[144:147], v70 offset:8640
	s_waitcnt lgkmcnt(3)
	v_mfma_f32_16x16x32_bf16 v[4:7], v[4:7], v[24:27], 0
	s_waitcnt lgkmcnt(2)
	v_mfma_f32_16x16x32_bf16 v[4:7], v[94:97], v[20:23], v[4:7]
	s_waitcnt lgkmcnt(1)
	v_mfma_f32_16x16x32_bf16 v[4:7], v[140:143], v[16:19], v[4:7]
	s_waitcnt lgkmcnt(0)
	v_mfma_f32_16x16x32_bf16 v[4:7], v[144:147], v[12:15], v[4:7]
	v_mfma_f32_16x16x32_bf16 v[94:97], v[8:11], v[32:35], 0
	s_nop 7
	ds_write2_b32 v73, v94, v98 offset1:16
	ds_write2_b32 v73, v95, v99 offset0:132 offset1:148
	ds_write2_b32 v74, v96, v100 offset0:8 offset1:24
	ds_write2_b32 v74, v97, v101 offset0:140 offset1:156
	v_mfma_f32_16x16x32_bf16 v[94:97], v[8:11], v[40:43], 0
	v_mfma_f32_16x16x32_bf16 v[98:101], v[8:11], v[36:39], 0
	s_nop 7
	ds_write2_b32 v73, v94, v98 offset0:32 offset1:48
	ds_write2_b32 v73, v95, v99 offset0:164 offset1:180
	ds_write2_b32 v74, v96, v100 offset0:40 offset1:56
	ds_write2_b32 v74, v97, v101 offset0:172 offset1:188
	v_mfma_f32_16x16x32_bf16 v[94:97], v[8:11], v[48:51], 0
	v_mfma_f32_16x16x32_bf16 v[98:101], v[8:11], v[44:47], 0
	s_nop 7
	ds_write2_b32 v73, v94, v98 offset0:64 offset1:80
	ds_write2_b32 v73, v95, v99 offset0:196 offset1:212
	ds_write2_b32 v74, v96, v100 offset0:72 offset1:88
	ds_write2_b32 v74, v97, v101 offset0:204 offset1:220
	v_mfma_f32_16x16x32_bf16 v[94:97], v[8:11], v[56:59], 0
	v_mfma_f32_16x16x32_bf16 v[8:11], v[8:11], v[52:55], 0
	s_nop 7
	ds_write2_b32 v73, v94, v8 offset0:96 offset1:112
	ds_write2_b32 v73, v95, v9 offset0:228 offset1:244
	ds_write2_b32 v74, v96, v10 offset0:104 offset1:120
	ds_write2_b32 v74, v97, v11 offset0:236 offset1:252
	s_waitcnt vmcnt(0) lgkmcnt(0)
	ds_read2st64_b32 v[8:9], v75 offset1:1
	ds_read2_b32 v[140:141], v75 offset0:132 offset1:196
	ds_read2st64_b32 v[142:143], v71 offset0:4 offset1:5
	ds_read2st64_b32 v[144:145], v78 offset0:6 offset1:7
	ds_read2st64_b32 v[146:147], v79 offset0:8 offset1:9
	ds_read2st64_b32 v[148:149], v82 offset0:10 offset1:11
	ds_read2st64_b32 v[150:151], v83 offset0:12 offset1:13
	ds_read2st64_b32 v[152:153], v84 offset0:14 offset1:15
	ds_read2st64_b32 v[154:155], v85 offset0:16 offset1:17
	ds_read2st64_b32 v[156:157], v86 offset0:18 offset1:19
	ds_read2st64_b32 v[158:159], v87 offset0:20 offset1:21
	ds_read2st64_b32 v[160:161], v88 offset0:22 offset1:23
	ds_read2st64_b32 v[162:163], v89 offset0:24 offset1:25
	ds_read2st64_b32 v[164:165], v91 offset0:26 offset1:27
	ds_read2st64_b32 v[166:167], v92 offset0:28 offset1:29
	ds_read2st64_b32 v[168:169], v93 offset0:30 offset1:31
	v_mov_b32_e32 v186, v102
	v_mov_b32_e32 v187, v103
	v_mfma_f32_16x16x32_bf16 v[32:35], v[60:63], v[32:35], 0
	s_waitcnt lgkmcnt(0)
	v_pk_fma_f32 v[184:185], v[66:67], v[186:187], v[8:9] op_sel:[1,1,0] op_sel_hi:[1,0,1] neg_lo:[1,0,0]
	v_pk_fma_f32 v[188:189], v[66:67], v[186:187], v[184:185] op_sel_hi:[0,1,1]
	v_cvt_pk_bf16_f32 v190, v188, v189
	v_and_b32_e32 v191, 63, v207
	v_lshl_add_u32 v191, v191, 1, v72
	ds_write_b32 v191, v190 offset:8448
	v_pk_fma_f32 v[184:185], v[66:67], v[188:189], v[140:141] op_sel:[1,1,0] op_sel_hi:[1,0,1] neg_lo:[1,0,0]
	v_pk_fma_f32 v[186:187], v[66:67], v[188:189], v[184:185] op_sel_hi:[0,1,1]
	v_cvt_pk_bf16_f32 v190, v186, v187
	ds_write_b32 v191, v190 offset:8720
	v_pk_fma_f32 v[184:185], v[66:67], v[186:187], v[142:143] op_sel:[1,1,0] op_sel_hi:[1,0,1] neg_lo:[1,0,0]
	v_pk_fma_f32 v[188:189], v[66:67], v[186:187], v[184:185] op_sel_hi:[0,1,1]
	v_cvt_pk_bf16_f32 v190, v188, v189
	ds_write_b32 v191, v190 offset:8992
	v_pk_fma_f32 v[184:185], v[66:67], v[188:189], v[144:145] op_sel:[1,1,0] op_sel_hi:[1,0,1] neg_lo:[1,0,0]
	v_pk_fma_f32 v[186:187], v[66:67], v[188:189], v[184:185] op_sel_hi:[0,1,1]
	v_cvt_pk_bf16_f32 v190, v186, v187
	ds_write_b32 v191, v190 offset:9264
	v_pk_fma_f32 v[184:185], v[66:67], v[186:187], v[146:147] op_sel:[1,1,0] op_sel_hi:[1,0,1] neg_lo:[1,0,0]
	v_pk_fma_f32 v[188:189], v[66:67], v[186:187], v[184:185] op_sel_hi:[0,1,1]
	v_cvt_pk_bf16_f32 v190, v188, v189
	ds_write_b32 v191, v190 offset:9536
	v_pk_fma_f32 v[184:185], v[66:67], v[188:189], v[148:149] op_sel:[1,1,0] op_sel_hi:[1,0,1] neg_lo:[1,0,0]
	v_pk_fma_f32 v[186:187], v[66:67], v[188:189], v[184:185] op_sel_hi:[0,1,1]
	v_cvt_pk_bf16_f32 v190, v186, v187
	ds_write_b32 v191, v190 offset:9808
	v_pk_fma_f32 v[184:185], v[66:67], v[186:187], v[150:151] op_sel:[1,1,0] op_sel_hi:[1,0,1] neg_lo:[1,0,0]
	v_pk_fma_f32 v[188:189], v[66:67], v[186:187], v[184:185] op_sel_hi:[0,1,1]
	v_cvt_pk_bf16_f32 v190, v188, v189
	ds_write_b32 v191, v190 offset:10080
	v_pk_fma_f32 v[184:185], v[66:67], v[188:189], v[152:153] op_sel:[1,1,0] op_sel_hi:[1,0,1] neg_lo:[1,0,0]
	v_pk_fma_f32 v[186:187], v[66:67], v[188:189], v[184:185] op_sel_hi:[0,1,1]
	v_cvt_pk_bf16_f32 v190, v186, v187
	ds_write_b32 v191, v190 offset:10352
	v_pk_fma_f32 v[184:185], v[66:67], v[186:187], v[154:155] op_sel:[1,1,0] op_sel_hi:[1,0,1] neg_lo:[1,0,0]
	v_pk_fma_f32 v[188:189], v[66:67], v[186:187], v[184:185] op_sel_hi:[0,1,1]
	v_cvt_pk_bf16_f32 v190, v188, v189
	ds_write_b32 v191, v190 offset:10624
	v_pk_fma_f32 v[184:185], v[66:67], v[188:189], v[156:157] op_sel:[1,1,0] op_sel_hi:[1,0,1] neg_lo:[1,0,0]
	v_pk_fma_f32 v[186:187], v[66:67], v[188:189], v[184:185] op_sel_hi:[0,1,1]
	v_cvt_pk_bf16_f32 v190, v186, v187
	ds_write_b32 v191, v190 offset:10896
	v_pk_fma_f32 v[184:185], v[66:67], v[186:187], v[158:159] op_sel:[1,1,0] op_sel_hi:[1,0,1] neg_lo:[1,0,0]
	v_pk_fma_f32 v[188:189], v[66:67], v[186:187], v[184:185] op_sel_hi:[0,1,1]
	v_cvt_pk_bf16_f32 v190, v188, v189
	ds_write_b32 v191, v190 offset:11168
	v_pk_fma_f32 v[184:185], v[66:67], v[188:189], v[160:161] op_sel:[1,1,0] op_sel_hi:[1,0,1] neg_lo:[1,0,0]
	v_pk_fma_f32 v[186:187], v[66:67], v[188:189], v[184:185] op_sel_hi:[0,1,1]
	v_cvt_pk_bf16_f32 v190, v186, v187
	ds_write_b32 v191, v190 offset:11440
	v_pk_fma_f32 v[184:185], v[66:67], v[186:187], v[162:163] op_sel:[1,1,0] op_sel_hi:[1,0,1] neg_lo:[1,0,0]
	v_pk_fma_f32 v[188:189], v[66:67], v[186:187], v[184:185] op_sel_hi:[0,1,1]
	v_cvt_pk_bf16_f32 v190, v188, v189
	ds_write_b32 v191, v190 offset:11712
	v_pk_fma_f32 v[184:185], v[66:67], v[188:189], v[164:165] op_sel:[1,1,0] op_sel_hi:[1,0,1] neg_lo:[1,0,0]
	v_pk_fma_f32 v[186:187], v[66:67], v[188:189], v[184:185] op_sel_hi:[0,1,1]
	v_cvt_pk_bf16_f32 v190, v186, v187
	ds_write_b32 v191, v190 offset:11984
	v_pk_fma_f32 v[184:185], v[66:67], v[186:187], v[166:167] op_sel:[1,1,0] op_sel_hi:[1,0,1] neg_lo:[1,0,0]
	v_pk_fma_f32 v[188:189], v[66:67], v[186:187], v[184:185] op_sel_hi:[0,1,1]
	v_cvt_pk_bf16_f32 v190, v188, v189
	ds_write_b32 v191, v190 offset:12256
	v_pk_fma_f32 v[184:185], v[66:67], v[188:189], v[168:169] op_sel:[1,1,0] op_sel_hi:[1,0,1] neg_lo:[1,0,0]
	v_pk_fma_f32 v[186:187], v[66:67], v[188:189], v[184:185] op_sel_hi:[0,1,1]
	v_mov_b32_e32 v98, v186
	v_mov_b32_e32 v99, v187
	v_cvt_pk_bf16_f32 v190, v186, v187
	ds_write_b32 v191, v190 offset:12528
	s_waitcnt vmcnt(0) lgkmcnt(0)
	ds_read_b128 v[8:11], v70 offset:8448
	ds_read_b128 v[94:97], v70 offset:8512
	s_waitcnt lgkmcnt(1)
	v_mfma_f32_16x16x32_bf16 v[8:11], v[8:11], v[24:27], 0
	s_waitcnt lgkmcnt(0)
	v_mfma_f32_16x16x32_bf16 v[8:11], v[94:97], v[20:23], v[8:11]
	ds_read_b128 v[94:97], v70 offset:8576
	s_waitcnt lgkmcnt(0)
	v_mfma_f32_16x16x32_bf16 v[8:11], v[94:97], v[16:19], v[8:11]
	ds_read_b128 v[94:97], v70 offset:8640
	ds_write2_b32 v73, v32, v28 offset1:16
	ds_write2_b32 v73, v33, v29 offset0:132 offset1:148
	ds_write2_b32 v74, v34, v30 offset0:8 offset1:24
	ds_write2_b32 v74, v35, v31 offset0:140 offset1:156
	v_mfma_f32_16x16x32_bf16 v[28:31], v[60:63], v[40:43], 0
	v_mov_b32_e32 v40, 0
	v_mov_b32_e32 v41, 0
	v_mov_b32_e32 v42, 0
	v_mfma_f32_16x16x32_bf16 v[32:35], v[60:63], v[36:39], 0
	s_nop 7
	ds_write2_b32 v73, v28, v32 offset0:32 offset1:48
	ds_write2_b32 v73, v29, v33 offset0:164 offset1:180
	ds_write2_b32 v74, v30, v34 offset0:40 offset1:56
	ds_write2_b32 v74, v31, v35 offset0:172 offset1:188
	v_mfma_f32_16x16x32_bf16 v[28:31], v[60:63], v[48:51], 0
	v_mov_b32_e32 v36, 0
	v_mov_b32_e32 v43, 0
	v_mfma_f32_16x16x32_bf16 v[32:35], v[60:63], v[44:47], 0
	s_nop 7
	ds_write2_b32 v73, v28, v32 offset0:64 offset1:80
	ds_write2_b32 v73, v29, v33 offset0:196 offset1:212
	ds_write2_b32 v74, v30, v34 offset0:72 offset1:88
	ds_write2_b32 v74, v31, v35 offset0:204 offset1:220
	v_mfma_f32_16x16x32_bf16 v[28:31], v[60:63], v[56:59], 0
	v_mfma_f32_16x16x32_bf16 v[32:35], v[60:63], v[52:55], 0
	s_nop 7
	ds_write2_b32 v73, v28, v32 offset0:96 offset1:112
	ds_write2_b32 v73, v29, v33 offset0:228 offset1:244
	ds_write2_b32 v74, v30, v34 offset0:104 offset1:120
	ds_write2_b32 v74, v31, v35 offset0:236 offset1:252
	s_waitcnt vmcnt(0) lgkmcnt(0)
	ds_read2st64_b32 v[28:29], v75 offset1:1
	ds_read2_b32 v[140:141], v75 offset0:132 offset1:196
	ds_read2st64_b32 v[142:143], v71 offset0:4 offset1:5
	ds_read2st64_b32 v[144:145], v78 offset0:6 offset1:7
	ds_read2st64_b32 v[146:147], v79 offset0:8 offset1:9
	ds_read2st64_b32 v[148:149], v82 offset0:10 offset1:11
	ds_read2st64_b32 v[150:151], v83 offset0:12 offset1:13
	ds_read2st64_b32 v[152:153], v84 offset0:14 offset1:15
	ds_read2st64_b32 v[154:155], v85 offset0:16 offset1:17
	ds_read2st64_b32 v[156:157], v86 offset0:18 offset1:19
	ds_read2st64_b32 v[158:159], v87 offset0:20 offset1:21
	ds_read2st64_b32 v[160:161], v88 offset0:22 offset1:23
	ds_read2st64_b32 v[162:163], v89 offset0:24 offset1:25
	ds_read2st64_b32 v[164:165], v91 offset0:26 offset1:27
	ds_read2st64_b32 v[166:167], v92 offset0:28 offset1:29
	ds_read2st64_b32 v[168:169], v93 offset0:30 offset1:31
	v_mov_b32_e32 v186, v98
	v_mov_b32_e32 v187, v99
	s_waitcnt lgkmcnt(0)
	v_mfma_f32_16x16x32_bf16 v[8:11], v[94:97], v[12:15], v[8:11]
	v_pk_fma_f32 v[184:185], v[66:67], v[186:187], v[28:29] op_sel:[1,1,0] op_sel_hi:[1,0,1] neg_lo:[1,0,0]
	v_pk_fma_f32 v[188:189], v[66:67], v[186:187], v[184:185] op_sel_hi:[0,1,1]
	v_cvt_pk_bf16_f32 v190, v188, v189
	v_and_b32_e32 v191, 63, v207
	v_lshl_add_u32 v191, v191, 1, v72
	ds_write_b32 v191, v190 offset:8448
	v_pk_fma_f32 v[184:185], v[66:67], v[188:189], v[140:141] op_sel:[1,1,0] op_sel_hi:[1,0,1] neg_lo:[1,0,0]
	v_pk_fma_f32 v[186:187], v[66:67], v[188:189], v[184:185] op_sel_hi:[0,1,1]
	v_cvt_pk_bf16_f32 v190, v186, v187
	ds_write_b32 v191, v190 offset:8720
	v_pk_fma_f32 v[184:185], v[66:67], v[186:187], v[142:143] op_sel:[1,1,0] op_sel_hi:[1,0,1] neg_lo:[1,0,0]
	v_pk_fma_f32 v[188:189], v[66:67], v[186:187], v[184:185] op_sel_hi:[0,1,1]
	v_cvt_pk_bf16_f32 v190, v188, v189
	ds_write_b32 v191, v190 offset:8992
	v_pk_fma_f32 v[184:185], v[66:67], v[188:189], v[144:145] op_sel:[1,1,0] op_sel_hi:[1,0,1] neg_lo:[1,0,0]
	v_pk_fma_f32 v[186:187], v[66:67], v[188:189], v[184:185] op_sel_hi:[0,1,1]
	v_cvt_pk_bf16_f32 v190, v186, v187
	ds_write_b32 v191, v190 offset:9264
	v_pk_fma_f32 v[184:185], v[66:67], v[186:187], v[146:147] op_sel:[1,1,0] op_sel_hi:[1,0,1] neg_lo:[1,0,0]
	v_pk_fma_f32 v[188:189], v[66:67], v[186:187], v[184:185] op_sel_hi:[0,1,1]
	v_cvt_pk_bf16_f32 v190, v188, v189
	ds_write_b32 v191, v190 offset:9536
	v_pk_fma_f32 v[184:185], v[66:67], v[188:189], v[148:149] op_sel:[1,1,0] op_sel_hi:[1,0,1] neg_lo:[1,0,0]
	v_pk_fma_f32 v[186:187], v[66:67], v[188:189], v[184:185] op_sel_hi:[0,1,1]
	v_cvt_pk_bf16_f32 v190, v186, v187
	ds_write_b32 v191, v190 offset:9808
	v_pk_fma_f32 v[184:185], v[66:67], v[186:187], v[150:151] op_sel:[1,1,0] op_sel_hi:[1,0,1] neg_lo:[1,0,0]
	v_pk_fma_f32 v[188:189], v[66:67], v[186:187], v[184:185] op_sel_hi:[0,1,1]
	v_cvt_pk_bf16_f32 v190, v188, v189
	ds_write_b32 v191, v190 offset:10080
	v_pk_fma_f32 v[184:185], v[66:67], v[188:189], v[152:153] op_sel:[1,1,0] op_sel_hi:[1,0,1] neg_lo:[1,0,0]
	v_pk_fma_f32 v[186:187], v[66:67], v[188:189], v[184:185] op_sel_hi:[0,1,1]
	v_cvt_pk_bf16_f32 v190, v186, v187
	ds_write_b32 v191, v190 offset:10352
	v_pk_fma_f32 v[184:185], v[66:67], v[186:187], v[154:155] op_sel:[1,1,0] op_sel_hi:[1,0,1] neg_lo:[1,0,0]
	v_pk_fma_f32 v[188:189], v[66:67], v[186:187], v[184:185] op_sel_hi:[0,1,1]
	v_cvt_pk_bf16_f32 v190, v188, v189
	ds_write_b32 v191, v190 offset:10624
	v_pk_fma_f32 v[184:185], v[66:67], v[188:189], v[156:157] op_sel:[1,1,0] op_sel_hi:[1,0,1] neg_lo:[1,0,0]
	v_pk_fma_f32 v[186:187], v[66:67], v[188:189], v[184:185] op_sel_hi:[0,1,1]
	v_cvt_pk_bf16_f32 v190, v186, v187
	ds_write_b32 v191, v190 offset:10896
	v_pk_fma_f32 v[184:185], v[66:67], v[186:187], v[158:159] op_sel:[1,1,0] op_sel_hi:[1,0,1] neg_lo:[1,0,0]
	v_pk_fma_f32 v[188:189], v[66:67], v[186:187], v[184:185] op_sel_hi:[0,1,1]
	v_cvt_pk_bf16_f32 v190, v188, v189
	ds_write_b32 v191, v190 offset:11168
	v_pk_fma_f32 v[184:185], v[66:67], v[188:189], v[160:161] op_sel:[1,1,0] op_sel_hi:[1,0,1] neg_lo:[1,0,0]
	v_pk_fma_f32 v[186:187], v[66:67], v[188:189], v[184:185] op_sel_hi:[0,1,1]
	v_cvt_pk_bf16_f32 v190, v186, v187
	ds_write_b32 v191, v190 offset:11440
	v_pk_fma_f32 v[184:185], v[66:67], v[186:187], v[162:163] op_sel:[1,1,0] op_sel_hi:[1,0,1] neg_lo:[1,0,0]
	v_pk_fma_f32 v[188:189], v[66:67], v[186:187], v[184:185] op_sel_hi:[0,1,1]
	v_cvt_pk_bf16_f32 v190, v188, v189
	ds_write_b32 v191, v190 offset:11712
	v_pk_fma_f32 v[184:185], v[66:67], v[188:189], v[164:165] op_sel:[1,1,0] op_sel_hi:[1,0,1] neg_lo:[1,0,0]
	v_pk_fma_f32 v[186:187], v[66:67], v[188:189], v[184:185] op_sel_hi:[0,1,1]
	v_cvt_pk_bf16_f32 v190, v186, v187
	ds_write_b32 v191, v190 offset:11984
	v_pk_fma_f32 v[184:185], v[66:67], v[186:187], v[166:167] op_sel:[1,1,0] op_sel_hi:[1,0,1] neg_lo:[1,0,0]
	v_pk_fma_f32 v[188:189], v[66:67], v[186:187], v[184:185] op_sel_hi:[0,1,1]
	v_cvt_pk_bf16_f32 v190, v188, v189
	ds_write_b32 v191, v190 offset:12256
	v_pk_fma_f32 v[184:185], v[66:67], v[188:189], v[168:169] op_sel:[1,1,0] op_sel_hi:[1,0,1] neg_lo:[1,0,0]
	v_pk_fma_f32 v[186:187], v[66:67], v[188:189], v[184:185] op_sel_hi:[0,1,1]
	v_mov_b32_e32 v28, v186
	v_mov_b32_e32 v29, v187
	v_cvt_pk_bf16_f32 v190, v186, v187
	ds_write_b32 v191, v190 offset:12528
	s_waitcnt vmcnt(0) lgkmcnt(0)
	ds_read_b128 v[28:31], v70 offset:8448
	s_waitcnt lgkmcnt(0)
	v_mfma_f32_16x16x32_bf16 v[24:27], v[28:31], v[24:27], 0
	ds_read_b128 v[28:31], v70 offset:8512
	s_add_u32 s0, s0, s1
	s_addc_u32 s1, s2, 0
	s_waitcnt lgkmcnt(0)
	v_mfma_f32_16x16x32_bf16 v[20:23], v[28:31], v[20:23], v[24:27]
	s_nop 2
	ds_read_b128 v[24:27], v70 offset:8576
	s_lshl_b64 s[0:1], s[0:1], 14
	s_waitcnt lgkmcnt(0)
	v_mfma_f32_16x16x32_bf16 v[16:19], v[24:27], v[16:19], v[20:23]
	s_nop 2
	ds_read_b128 v[20:23], v70 offset:8640
	s_waitcnt lgkmcnt(0)
	v_mfma_f32_16x16x32_bf16 v[12:15], v[20:23], v[12:15], v[16:19]
	s_nop 2
	v_lshl_add_u64 v[16:17], v[64:65], 0, s[0:1]
	v_mov_b32_e32 v20, v207
	global_load_dwordx2 v[84:85], v[16:17], off
	v_add_u32_e32 v16, s90, v77
	v_and_b32_e32 v91, 63, v20
	v_or_b32_e32 v16, v91, v16
	v_ashrrev_i32_e32 v17, 31, v16
	v_lshl_add_u64 v[16:17], v[16:17], 3, s[60:61]
	global_load_dwordx2 v[82:83], v[16:17], off
	v_add_u32_e32 v16, s91, v76
	v_ashrrev_i32_e32 v17, 31, v16
	v_and_b32_e32 v92, 15, v20
	v_lshlrev_b64 v[16:17], 12, v[16:17]
	v_lshl_add_u64 v[18:19], s[62:63], 0, v[16:17]
	v_lshlrev_b32_e32 v21, 4, v92
	v_and_b32_e32 v128, 48, v20
	v_cmp_gt_u32_e64 s[42:43], 32, v91
	v_lshl_add_u64 v[18:19], v[18:19], 0, v[128:129]
	v_lshlrev_b32_e32 v128, 1, v21
	s_and_saveexec_b64 s[0:1], s[42:43]
	s_cbranch_execz .LBB0_1789
	v_lshl_add_u64 v[22:23], v[18:19], 0, v[128:129]
	global_load_dwordx4 v[40:43], v[22:23], off

.LBB0_1811:
	s_or_b64 exec, exec, s[0:1]
	s_waitcnt vmcnt(0) lgkmcnt(0)
	v_mov_b32_e32 v158, 0x5040100
	v_mov_b32_e32 v159, 0x7060302
	v_perm_b32 v32, v142, v140, v158
	v_perm_b32 v33, v142, v140, v159
	v_perm_b32 v34, v143, v141, v158
	v_perm_b32 v35, v143, v141, v159
	v_perm_b32 v28, v146, v144, v158
	v_perm_b32 v29, v146, v144, v159
	v_perm_b32 v30, v147, v145, v158
	v_perm_b32 v31, v147, v145, v159
	v_perm_b32 v24, v150, v148, v158
	v_perm_b32 v25, v150, v148, v159
	v_perm_b32 v26, v151, v149, v158
	v_perm_b32 v27, v151, v149, v159
	v_perm_b32 v20, v154, v152, v158
	v_perm_b32 v21, v154, v152, v159
	v_perm_b32 v22, v155, v153, v158
	v_perm_b32 v23, v155, v153, v159
	v_mfma_f32_16x16x32_bf16 v[94:97], v[16:19], v[40:43], 0
	v_mul_u32_u24_e32 v86, 0x210, v93
	v_lshlrev_b32_e32 v87, 2, v92
	v_lshlrev_b32_e32 v86, 2, v86
	v_mfma_f32_16x16x32_bf16 v[98:101], v[16:19], v[36:39], 0
	v_add3_u32 v88, v81, v87, v86
	v_add_u32_e32 v89, 0x400, v88
	v_mul_u32_u24_e32 v103, 0x110, v92
	s_nop 4
	ds_write2_b32 v88, v94, v98 offset1:16
	ds_write2_b32 v88, v95, v99 offset0:132 offset1:148
	ds_write2_b32 v89, v96, v100 offset0:8 offset1:24
	ds_write2_b32 v89, v97, v101 offset0:140 offset1:156
	v_mfma_f32_16x16x32_bf16 v[92:95], v[16:19], v[48:51], 0
	v_lshl_add_u32 v87, v91, 2, v81
	v_add3_u32 v81, v81, v128, v103
	v_pk_add_f32 v[0:1], v[0:1], 0 op_sel_hi:[1,0]
	v_mfma_f32_16x16x32_bf16 v[96:99], v[16:19], v[44:47], 0
	s_nop 7
	ds_write2_b32 v88, v92, v96 offset0:32 offset1:48
	ds_write2_b32 v88, v93, v97 offset0:164 offset1:180
	ds_write2_b32 v89, v94, v98 offset0:40 offset1:56
	ds_write2_b32 v89, v95, v99 offset0:172 offset1:188
	v_mfma_f32_16x16x32_bf16 v[92:95], v[16:19], v[56:59], 0
	v_readlane_b32 s68, v251, 41
	v_readlane_b32 s76, v251, 49
	v_readlane_b32 s77, v251, 50
	v_mfma_f32_16x16x32_bf16 v[96:99], v[16:19], v[52:55], 0
	s_nop 7
	ds_write2_b32 v88, v92, v96 offset0:64 offset1:80
	ds_write2_b32 v88, v93, v97 offset0:196 offset1:212
	ds_write2_b32 v89, v94, v98 offset0:72 offset1:88
	ds_write2_b32 v89, v95, v99 offset0:204 offset1:220
	v_mfma_f32_16x16x32_bf16 v[92:95], v[16:19], v[64:67], 0
	s_mov_b32 s10, 0x3f200000
	v_readlane_b32 s69, v251, 42
	v_readlane_b32 s70, v251, 43
	v_mfma_f32_16x16x32_bf16 v[16:19], v[16:19], v[60:63], 0
	s_nop 7
	ds_write2_b32 v88, v92, v16 offset0:96 offset1:112
	ds_write2_b32 v88, v93, v17 offset0:228 offset1:244
	ds_write2_b32 v89, v94, v18 offset0:104 offset1:120
	ds_write2_b32 v89, v95, v19 offset0:236 offset1:252
	v_lshlrev_b32_e32 v16, 1, v91
	v_add_u32_e32 v91, 0xf0, v87
	s_waitcnt vmcnt(0) lgkmcnt(0)
	v_sub_u32_e32 v86, v87, v16
	ds_read2st64_b32 v[16:17], v91 offset0:30 offset1:31
	v_add_u32_e32 v140, 0xe0, v87
	ds_read2st64_b32 v[142:143], v140 offset0:28 offset1:29
	v_add_u32_e32 v141, 0xd0, v87
	ds_read2st64_b32 v[144:145], v141 offset0:26 offset1:27
	v_add_u32_e32 v146, 0xc0, v87
	ds_read2st64_b32 v[148:149], v146 offset0:24 offset1:25
	v_add_u32_e32 v147, 0xb0, v87
	ds_read2st64_b32 v[150:151], v147 offset0:22 offset1:23
	v_add_u32_e32 v152, 0xa0, v87
	ds_read2st64_b32 v[154:155], v152 offset0:20 offset1:21
	v_add_u32_e32 v153, 0x90, v87
	ds_read2st64_b32 v[156:157], v153 offset0:18 offset1:19
	v_add_u32_e32 v158, 0x80, v87
	ds_read2st64_b32 v[160:161], v158 offset0:16 offset1:17
	v_add_u32_e32 v159, 0x70, v87
	ds_read2st64_b32 v[162:163], v159 offset0:14 offset1:15
	v_add_u32_e32 v164, 0x60, v87
	ds_read2st64_b32 v[166:167], v164 offset0:12 offset1:13
	v_add_u32_e32 v165, 0x50, v87
	ds_read2st64_b32 v[168:169], v165 offset0:10 offset1:11
	v_add_u32_e32 v170, 64, v87
	ds_read2st64_b32 v[172:173], v170 offset0:8 offset1:9
	v_add_u32_e32 v171, 48, v87
	ds_read2st64_b32 v[174:175], v171 offset0:6 offset1:7
	v_add_u32_e32 v176, 32, v87
	ds_read2st64_b32 v[178:179], v176 offset0:4 offset1:5
	ds_read2_b32 v[180:181], v87 offset0:132 offset1:196
	ds_read2st64_b32 v[182:183], v87 offset1:1
	v_mov_b32_e32 v186, v84
	v_mov_b32_e32 v187, v85
	v_mfma_f32_16x16x32_bf16 v[108:111], v[72:75], v[36:39], 0
	v_readlane_b32 s71, v251, 44
	s_waitcnt lgkmcnt(0)
	v_pk_fma_f32 v[184:185], v[82:83], v[186:187], v[16:17] op_sel:[1,1,0] op_sel_hi:[1,0,1] neg_lo:[1,0,0]
	v_pk_fma_f32 v[188:189], v[82:83], v[186:187], v[184:185] op_sel_hi:[0,1,1]
	v_cvt_pk_bf16_f32 v190, v188, v189
	v_and_b32_e32 v191, 63, v207
	v_lshl_add_u32 v191, v191, 1, v86
	ds_write_b32 v191, v190 offset:12528
	v_add_u32_e32 v84, 0xe0, v87
	v_readlane_b32 s72, v251, 45
	v_readlane_b32 s73, v251, 46
	v_pk_fma_f32 v[184:185], v[82:83], v[188:189], v[142:143] op_sel:[1,1,0] op_sel_hi:[1,0,1] neg_lo:[1,0,0]
	v_pk_fma_f32 v[186:187], v[82:83], v[188:189], v[184:185] op_sel_hi:[0,1,1]
	v_cvt_pk_bf16_f32 v190, v186, v187
	ds_write_b32 v191, v190 offset:12256
	v_add_u32_e32 v85, 0xd0, v87
	v_readlane_b32 s74, v251, 47
	v_readlane_b32 s75, v251, 48
	v_pk_fma_f32 v[184:185], v[82:83], v[186:187], v[144:145] op_sel:[1,1,0] op_sel_hi:[1,0,1] neg_lo:[1,0,0]
	v_pk_fma_f32 v[188:189], v[82:83], v[186:187], v[184:185] op_sel_hi:[0,1,1]
	v_cvt_pk_bf16_f32 v190, v188, v189
	ds_write_b32 v191, v190 offset:11984
	v_add_u32_e32 v92, 0xc0, v87
	v_readlane_b32 s78, v251, 51
	v_readlane_b32 s79, v251, 52
	v_pk_fma_f32 v[184:185], v[82:83], v[188:189], v[148:149] op_sel:[1,1,0] op_sel_hi:[1,0,1] neg_lo:[1,0,0]
	v_pk_fma_f32 v[186:187], v[82:83], v[188:189], v[184:185] op_sel_hi:[0,1,1]
	v_cvt_pk_bf16_f32 v190, v186, v187
	ds_write_b32 v191, v190 offset:11712
	v_add_u32_e32 v93, 0xb0, v87
	v_readlane_b32 s80, v251, 53
	v_readlane_b32 s81, v251, 54
	v_pk_fma_f32 v[184:185], v[82:83], v[186:187], v[150:151] op_sel:[1,1,0] op_sel_hi:[1,0,1] neg_lo:[1,0,0]
	v_pk_fma_f32 v[188:189], v[82:83], v[186:187], v[184:185] op_sel_hi:[0,1,1]
	v_cvt_pk_bf16_f32 v190, v188, v189
	ds_write_b32 v191, v190 offset:11440
	v_add_u32_e32 v94, 0xa0, v87
	v_readlane_b32 s82, v251, 55
	v_readlane_b32 s83, v251, 56
	v_pk_fma_f32 v[184:185], v[82:83], v[188:189], v[154:155] op_sel:[1,1,0] op_sel_hi:[1,0,1] neg_lo:[1,0,0]
	v_pk_fma_f32 v[186:187], v[82:83], v[188:189], v[184:185] op_sel_hi:[0,1,1]
	v_cvt_pk_bf16_f32 v190, v186, v187
	ds_write_b32 v191, v190 offset:11168
	v_add_u32_e32 v95, 0x90, v87
	v_pk_fma_f32 v[184:185], v[82:83], v[186:187], v[156:157] op_sel:[1,1,0] op_sel_hi:[1,0,1] neg_lo:[1,0,0]
	v_pk_fma_f32 v[188:189], v[82:83], v[186:187], v[184:185] op_sel_hi:[0,1,1]
	v_cvt_pk_bf16_f32 v190, v188, v189
	ds_write_b32 v191, v190 offset:10896
	v_add_u32_e32 v96, 0x80, v87
	v_pk_fma_f32 v[184:185], v[82:83], v[188:189], v[160:161] op_sel:[1,1,0] op_sel_hi:[1,0,1] neg_lo:[1,0,0]
	v_pk_fma_f32 v[186:187], v[82:83], v[188:189], v[184:185] op_sel_hi:[0,1,1]
	v_cvt_pk_bf16_f32 v190, v186, v187
	ds_write_b32 v191, v190 offset:10624
	v_add_u32_e32 v97, 0x70, v87
	v_pk_fma_f32 v[184:185], v[82:83], v[186:187], v[162:163] op_sel:[1,1,0] op_sel_hi:[1,0,1] neg_lo:[1,0,0]
	v_pk_fma_f32 v[188:189], v[82:83], v[186:187], v[184:185] op_sel_hi:[0,1,1]
	v_cvt_pk_bf16_f32 v190, v188, v189
	ds_write_b32 v191, v190 offset:10352
	v_add_u32_e32 v98, 0x60, v87
	v_pk_fma_f32 v[184:185], v[82:83], v[188:189], v[166:167] op_sel:[1,1,0] op_sel_hi:[1,0,1] neg_lo:[1,0,0]
	v_pk_fma_f32 v[186:187], v[82:83], v[188:189], v[184:185] op_sel_hi:[0,1,1]
	v_cvt_pk_bf16_f32 v190, v186, v187
	ds_write_b32 v191, v190 offset:10080
	v_add_u32_e32 v99, 0x50, v87
	v_pk_fma_f32 v[184:185], v[82:83], v[186:187], v[168:169] op_sel:[1,1,0] op_sel_hi:[1,0,1] neg_lo:[1,0,0]
	v_pk_fma_f32 v[188:189], v[82:83], v[186:187], v[184:185] op_sel_hi:[0,1,1]
	v_cvt_pk_bf16_f32 v190, v188, v189
	ds_write_b32 v191, v190 offset:9808
	v_add_u32_e32 v100, 64, v87
	v_pk_fma_f32 v[184:185], v[82:83], v[188:189], v[172:173] op_sel:[1,1,0] op_sel_hi:[1,0,1] neg_lo:[1,0,0]
	v_pk_fma_f32 v[186:187], v[82:83], v[188:189], v[184:185] op_sel_hi:[0,1,1]
	v_cvt_pk_bf16_f32 v190, v186, v187
	ds_write_b32 v191, v190 offset:9536
	v_add_u32_e32 v101, 48, v87
	v_pk_fma_f32 v[184:185], v[82:83], v[186:187], v[174:175] op_sel:[1,1,0] op_sel_hi:[1,0,1] neg_lo:[1,0,0]
	v_pk_fma_f32 v[188:189], v[82:83], v[186:187], v[184:185] op_sel_hi:[0,1,1]
	v_cvt_pk_bf16_f32 v190, v188, v189
	ds_write_b32 v191, v190 offset:9264
	v_add_u32_e32 v102, 32, v87
	v_pk_fma_f32 v[184:185], v[82:83], v[188:189], v[178:179] op_sel:[1,1,0] op_sel_hi:[1,0,1] neg_lo:[1,0,0]
	v_pk_fma_f32 v[186:187], v[82:83], v[188:189], v[184:185] op_sel_hi:[0,1,1]
	v_cvt_pk_bf16_f32 v190, v186, v187
	ds_write_b32 v191, v190 offset:8992
	v_pk_fma_f32 v[184:185], v[82:83], v[186:187], v[180:181] op_sel:[1,1,0] op_sel_hi:[1,0,1] neg_lo:[1,0,0]
	v_pk_fma_f32 v[188:189], v[82:83], v[186:187], v[184:185] op_sel_hi:[0,1,1]
	v_cvt_pk_bf16_f32 v190, v188, v189
	ds_write_b32 v191, v190 offset:8720
	v_pk_fma_f32 v[184:185], v[82:83], v[188:189], v[182:183] op_sel:[1,1,0] op_sel_hi:[1,0,1] neg_lo:[1,0,0]
	v_pk_fma_f32 v[186:187], v[82:83], v[188:189], v[184:185] op_sel_hi:[0,1,1]
	v_mov_b32_e32 v112, v186
	v_mov_b32_e32 v113, v187
	v_cvt_pk_bf16_f32 v190, v186, v187
	ds_write_b32 v191, v190 offset:8448
	s_waitcnt vmcnt(0) lgkmcnt(0)
	ds_read_b128 v[16:19], v81 offset:8448
	ds_read_b128 v[104:107], v81 offset:8512
	ds_read_b128 v[140:143], v81 offset:8576
	ds_read_b128 v[144:147], v81 offset:8640
	s_waitcnt lgkmcnt(3)
	v_mfma_f32_16x16x32_bf16 v[16:19], v[16:19], v[32:35], 0
	s_waitcnt lgkmcnt(2)
	v_mfma_f32_16x16x32_bf16 v[16:19], v[104:107], v[28:31], v[16:19]
	s_waitcnt lgkmcnt(1)
	v_mfma_f32_16x16x32_bf16 v[16:19], v[140:143], v[24:27], v[16:19]
	s_waitcnt lgkmcnt(0)
	v_mfma_f32_16x16x32_bf16 v[16:19], v[144:147], v[20:23], v[16:19]
	v_mfma_f32_16x16x32_bf16 v[104:107], v[72:75], v[40:43], 0
	s_nop 7
	ds_write2_b32 v88, v104, v108 offset1:16
	ds_write2_b32 v88, v105, v109 offset0:132 offset1:148
	ds_write2_b32 v89, v106, v110 offset0:8 offset1:24
	ds_write2_b32 v89, v107, v111 offset0:140 offset1:156
	v_mfma_f32_16x16x32_bf16 v[104:107], v[72:75], v[48:51], 0
	v_mfma_f32_16x16x32_bf16 v[108:111], v[72:75], v[44:47], 0
	s_nop 7
	ds_write2_b32 v88, v104, v108 offset0:32 offset1:48
	ds_write2_b32 v88, v105, v109 offset0:164 offset1:180
	ds_write2_b32 v89, v106, v110 offset0:40 offset1:56
	ds_write2_b32 v89, v107, v111 offset0:172 offset1:188
	v_mfma_f32_16x16x32_bf16 v[104:107], v[72:75], v[56:59], 0
	v_mfma_f32_16x16x32_bf16 v[108:111], v[72:75], v[52:55], 0
	s_nop 7
	ds_write2_b32 v88, v104, v108 offset0:64 offset1:80
	ds_write2_b32 v88, v105, v109 offset0:196 offset1:212
	ds_write2_b32 v89, v106, v110 offset0:72 offset1:88
	ds_write2_b32 v89, v107, v111 offset0:204 offset1:220
	v_mfma_f32_16x16x32_bf16 v[104:107], v[72:75], v[64:67], 0
	v_mfma_f32_16x16x32_bf16 v[72:75], v[72:75], v[60:63], 0
	s_nop 7
	ds_write2_b32 v88, v104, v72 offset0:96 offset1:112
	ds_write2_b32 v88, v105, v73 offset0:228 offset1:244
	ds_write2_b32 v89, v106, v74 offset0:104 offset1:120
	ds_write2_b32 v89, v107, v75 offset0:236 offset1:252
	s_waitcnt vmcnt(0) lgkmcnt(0)
	ds_read2st64_b32 v[72:73], v91 offset0:30 offset1:31
	ds_read2st64_b32 v[140:141], v84 offset0:28 offset1:29
	ds_read2st64_b32 v[142:143], v85 offset0:26 offset1:27
	ds_read2st64_b32 v[144:145], v92 offset0:24 offset1:25
	ds_read2st64_b32 v[146:147], v93 offset0:22 offset1:23
	ds_read2st64_b32 v[148:149], v94 offset0:20 offset1:21
	ds_read2st64_b32 v[150:151], v95 offset0:18 offset1:19
	ds_read2st64_b32 v[152:153], v96 offset0:16 offset1:17
	ds_read2st64_b32 v[154:155], v97 offset0:14 offset1:15
	ds_read2st64_b32 v[156:157], v98 offset0:12 offset1:13
	ds_read2st64_b32 v[158:159], v99 offset0:10 offset1:11
	ds_read2st64_b32 v[160:161], v100 offset0:8 offset1:9
	ds_read2st64_b32 v[162:163], v101 offset0:6 offset1:7
	ds_read2st64_b32 v[164:165], v102 offset0:4 offset1:5
	ds_read2_b32 v[166:167], v87 offset0:132 offset1:196
	ds_read2st64_b32 v[168:169], v87 offset1:1
	v_mov_b32_e32 v186, v112
	v_mov_b32_e32 v187, v113
	v_mfma_f32_16x16x32_bf16 v[108:111], v[76:79], v[36:39], 0
	s_waitcnt lgkmcnt(0)
	v_pk_fma_f32 v[184:185], v[82:83], v[186:187], v[72:73] op_sel:[1,1,0] op_sel_hi:[1,0,1] neg_lo:[1,0,0]
	v_pk_fma_f32 v[188:189], v[82:83], v[186:187], v[184:185] op_sel_hi:[0,1,1]
	v_cvt_pk_bf16_f32 v190, v188, v189
	v_and_b32_e32 v191, 63, v207
	v_lshl_add_u32 v191, v191, 1, v86
	ds_write_b32 v191, v190 offset:12528
	v_mfma_f32_16x16x32_bf16 v[36:39], v[68:71], v[36:39], 0
	v_pk_fma_f32 v[184:185], v[82:83], v[188:189], v[140:141] op_sel:[1,1,0] op_sel_hi:[1,0,1] neg_lo:[1,0,0]
	v_pk_fma_f32 v[186:187], v[82:83], v[188:189], v[184:185] op_sel_hi:[0,1,1]
	v_cvt_pk_bf16_f32 v190, v186, v187
	ds_write_b32 v191, v190 offset:12256
	v_pk_fma_f32 v[184:185], v[82:83], v[186:187], v[142:143] op_sel:[1,1,0] op_sel_hi:[1,0,1] neg_lo:[1,0,0]
	v_pk_fma_f32 v[188:189], v[82:83], v[186:187], v[184:185] op_sel_hi:[0,1,1]
	v_cvt_pk_bf16_f32 v190, v188, v189
	ds_write_b32 v191, v190 offset:11984
	v_pk_fma_f32 v[184:185], v[82:83], v[188:189], v[144:145] op_sel:[1,1,0] op_sel_hi:[1,0,1] neg_lo:[1,0,0]
	v_pk_fma_f32 v[186:187], v[82:83], v[188:189], v[184:185] op_sel_hi:[0,1,1]
	v_cvt_pk_bf16_f32 v190, v186, v187
	ds_write_b32 v191, v190 offset:11712
	v_pk_fma_f32 v[184:185], v[82:83], v[186:187], v[146:147] op_sel:[1,1,0] op_sel_hi:[1,0,1] neg_lo:[1,0,0]
	v_pk_fma_f32 v[188:189], v[82:83], v[186:187], v[184:185] op_sel_hi:[0,1,1]
	v_cvt_pk_bf16_f32 v190, v188, v189
	ds_write_b32 v191, v190 offset:11440
	v_pk_fma_f32 v[184:185], v[82:83], v[188:189], v[148:149] op_sel:[1,1,0] op_sel_hi:[1,0,1] neg_lo:[1,0,0]
	v_pk_fma_f32 v[186:187], v[82:83], v[188:189], v[184:185] op_sel_hi:[0,1,1]
	v_cvt_pk_bf16_f32 v190, v186, v187
	ds_write_b32 v191, v190 offset:11168
	v_pk_fma_f32 v[184:185], v[82:83], v[186:187], v[150:151] op_sel:[1,1,0] op_sel_hi:[1,0,1] neg_lo:[1,0,0]
	v_pk_fma_f32 v[188:189], v[82:83], v[186:187], v[184:185] op_sel_hi:[0,1,1]
	v_cvt_pk_bf16_f32 v190, v188, v189
	ds_write_b32 v191, v190 offset:10896
	v_pk_fma_f32 v[184:185], v[82:83], v[188:189], v[152:153] op_sel:[1,1,0] op_sel_hi:[1,0,1] neg_lo:[1,0,0]
	v_pk_fma_f32 v[186:187], v[82:83], v[188:189], v[184:185] op_sel_hi:[0,1,1]
	v_cvt_pk_bf16_f32 v190, v186, v187
	ds_write_b32 v191, v190 offset:10624
	v_pk_fma_f32 v[184:185], v[82:83], v[186:187], v[154:155] op_sel:[1,1,0] op_sel_hi:[1,0,1] neg_lo:[1,0,0]
	v_pk_fma_f32 v[188:189], v[82:83], v[186:187], v[184:185] op_sel_hi:[0,1,1]
	v_cvt_pk_bf16_f32 v190, v188, v189
	ds_write_b32 v191, v190 offset:10352
	v_pk_fma_f32 v[184:185], v[82:83], v[188:189], v[156:157] op_sel:[1,1,0] op_sel_hi:[1,0,1] neg_lo:[1,0,0]
	v_pk_fma_f32 v[186:187], v[82:83], v[188:189], v[184:185] op_sel_hi:[0,1,1]
	v_cvt_pk_bf16_f32 v190, v186, v187
	ds_write_b32 v191, v190 offset:10080
	v_pk_fma_f32 v[184:185], v[82:83], v[186:187], v[158:159] op_sel:[1,1,0] op_sel_hi:[1,0,1] neg_lo:[1,0,0]
	v_pk_fma_f32 v[188:189], v[82:83], v[186:187], v[184:185] op_sel_hi:[0,1,1]
	v_cvt_pk_bf16_f32 v190, v188, v189
	ds_write_b32 v191, v190 offset:9808
	v_pk_fma_f32 v[184:185], v[82:83], v[188:189], v[160:161] op_sel:[1,1,0] op_sel_hi:[1,0,1] neg_lo:[1,0,0]
	v_pk_fma_f32 v[186:187], v[82:83], v[188:189], v[184:185] op_sel_hi:[0,1,1]
	v_cvt_pk_bf16_f32 v190, v186, v187
	ds_write_b32 v191, v190 offset:9536
	v_pk_fma_f32 v[184:185], v[82:83], v[186:187], v[162:163] op_sel:[1,1,0] op_sel_hi:[1,0,1] neg_lo:[1,0,0]
	v_pk_fma_f32 v[188:189], v[82:83], v[186:187], v[184:185] op_sel_hi:[0,1,1]
	v_cvt_pk_bf16_f32 v190, v188, v189
	ds_write_b32 v191, v190 offset:9264
	v_pk_fma_f32 v[184:185], v[82:83], v[188:189], v[164:165] op_sel:[1,1,0] op_sel_hi:[1,0,1] neg_lo:[1,0,0]
	v_pk_fma_f32 v[186:187], v[82:83], v[188:189], v[184:185] op_sel_hi:[0,1,1]
	v_cvt_pk_bf16_f32 v190, v186, v187
	ds_write_b32 v191, v190 offset:8992
	v_pk_fma_f32 v[184:185], v[82:83], v[186:187], v[166:167] op_sel:[1,1,0] op_sel_hi:[1,0,1] neg_lo:[1,0,0]
	v_pk_fma_f32 v[188:189], v[82:83], v[186:187], v[184:185] op_sel_hi:[0,1,1]
	v_cvt_pk_bf16_f32 v190, v188, v189
	ds_write_b32 v191, v190 offset:8720
	v_pk_fma_f32 v[184:185], v[82:83], v[188:189], v[168:169] op_sel:[1,1,0] op_sel_hi:[1,0,1] neg_lo:[1,0,0]
	v_pk_fma_f32 v[186:187], v[82:83], v[188:189], v[184:185] op_sel_hi:[0,1,1]
	v_mov_b32_e32 v103, v186
	v_mov_b32_e32 v112, v187
	v_cvt_pk_bf16_f32 v190, v186, v187
	ds_write_b32 v191, v190 offset:8448
	s_waitcnt vmcnt(0) lgkmcnt(0)
	ds_read_b128 v[72:75], v81 offset:8448
	ds_read_b128 v[104:107], v81 offset:8512
	ds_read_b128 v[140:143], v81 offset:8576
	ds_read_b128 v[144:147], v81 offset:8640
	s_waitcnt lgkmcnt(3)
	v_mfma_f32_16x16x32_bf16 v[72:75], v[72:75], v[32:35], 0
	s_waitcnt lgkmcnt(2)
	v_mfma_f32_16x16x32_bf16 v[72:75], v[104:107], v[28:31], v[72:75]
	s_waitcnt lgkmcnt(1)
	v_mfma_f32_16x16x32_bf16 v[72:75], v[140:143], v[24:27], v[72:75]
	s_waitcnt lgkmcnt(0)
	v_mfma_f32_16x16x32_bf16 v[72:75], v[144:147], v[20:23], v[72:75]
	v_mfma_f32_16x16x32_bf16 v[104:107], v[76:79], v[40:43], 0
	s_nop 7
	ds_write2_b32 v88, v104, v108 offset1:16
	ds_write2_b32 v88, v105, v109 offset0:132 offset1:148
	ds_write2_b32 v89, v106, v110 offset0:8 offset1:24
	ds_write2_b32 v89, v107, v111 offset0:140 offset1:156
	v_mfma_f32_16x16x32_bf16 v[104:107], v[76:79], v[48:51], 0
	v_mfma_f32_16x16x32_bf16 v[108:111], v[76:79], v[44:47], 0
	s_nop 7
	ds_write2_b32 v88, v104, v108 offset0:32 offset1:48
	ds_write2_b32 v88, v105, v109 offset0:164 offset1:180
	ds_write2_b32 v89, v106, v110 offset0:40 offset1:56
	ds_write2_b32 v89, v107, v111 offset0:172 offset1:188
	v_mfma_f32_16x16x32_bf16 v[104:107], v[76:79], v[56:59], 0
	v_mfma_f32_16x16x32_bf16 v[108:111], v[76:79], v[52:55], 0
	s_nop 7
	ds_write2_b32 v88, v104, v108 offset0:64 offset1:80
	ds_write2_b32 v88, v105, v109 offset0:196 offset1:212
	ds_write2_b32 v89, v106, v110 offset0:72 offset1:88
	ds_write2_b32 v89, v107, v111 offset0:204 offset1:220
	v_mfma_f32_16x16x32_bf16 v[104:107], v[76:79], v[64:67], 0
	v_mfma_f32_16x16x32_bf16 v[76:79], v[76:79], v[60:63], 0
	s_nop 7
	ds_write2_b32 v88, v104, v76 offset0:96 offset1:112
	ds_write2_b32 v88, v105, v77 offset0:228 offset1:244
	ds_write2_b32 v89, v106, v78 offset0:104 offset1:120
	ds_write2_b32 v89, v107, v79 offset0:236 offset1:252
	s_waitcnt vmcnt(0) lgkmcnt(0)
	ds_read2st64_b32 v[76:77], v91 offset0:30 offset1:31
	ds_read2st64_b32 v[140:141], v84 offset0:28 offset1:29
	ds_read2st64_b32 v[142:143], v85 offset0:26 offset1:27
	ds_read2st64_b32 v[144:145], v92 offset0:24 offset1:25
	ds_read2st64_b32 v[146:147], v93 offset0:22 offset1:23
	ds_read2st64_b32 v[148:149], v94 offset0:20 offset1:21
	ds_read2st64_b32 v[150:151], v95 offset0:18 offset1:19
	ds_read2st64_b32 v[152:153], v96 offset0:16 offset1:17
	ds_read2st64_b32 v[154:155], v97 offset0:14 offset1:15
	ds_read2st64_b32 v[156:157], v98 offset0:12 offset1:13
	ds_read2st64_b32 v[158:159], v99 offset0:10 offset1:11
	ds_read2st64_b32 v[160:161], v100 offset0:8 offset1:9
	ds_read2st64_b32 v[162:163], v101 offset0:6 offset1:7
	ds_read2st64_b32 v[164:165], v102 offset0:4 offset1:5
	ds_read2_b32 v[166:167], v87 offset0:132 offset1:196
	ds_read2st64_b32 v[168:169], v87 offset1:1
	v_mov_b32_e32 v186, v103
	v_mov_b32_e32 v187, v112
	v_mfma_f32_16x16x32_bf16 v[40:43], v[68:71], v[40:43], 0
	s_waitcnt lgkmcnt(0)
	v_pk_fma_f32 v[184:185], v[82:83], v[186:187], v[76:77] op_sel:[1,1,0] op_sel_hi:[1,0,1] neg_lo:[1,0,0]
	v_pk_fma_f32 v[188:189], v[82:83], v[186:187], v[184:185] op_sel_hi:[0,1,1]
	v_cvt_pk_bf16_f32 v190, v188, v189
	v_and_b32_e32 v191, 63, v207
	v_lshl_add_u32 v191, v191, 1, v86
	ds_write_b32 v191, v190 offset:12528
	v_pk_fma_f32 v[184:185], v[82:83], v[188:189], v[140:141] op_sel:[1,1,0] op_sel_hi:[1,0,1] neg_lo:[1,0,0]
	v_pk_fma_f32 v[186:187], v[82:83], v[188:189], v[184:185] op_sel_hi:[0,1,1]
	v_cvt_pk_bf16_f32 v190, v186, v187
	ds_write_b32 v191, v190 offset:12256
	v_pk_fma_f32 v[184:185], v[82:83], v[186:187], v[142:143] op_sel:[1,1,0] op_sel_hi:[1,0,1] neg_lo:[1,0,0]
	v_pk_fma_f32 v[188:189], v[82:83], v[186:187], v[184:185] op_sel_hi:[0,1,1]
	v_cvt_pk_bf16_f32 v190, v188, v189
	ds_write_b32 v191, v190 offset:11984
	v_pk_fma_f32 v[184:185], v[82:83], v[188:189], v[144:145] op_sel:[1,1,0] op_sel_hi:[1,0,1] neg_lo:[1,0,0]
	v_pk_fma_f32 v[186:187], v[82:83], v[188:189], v[184:185] op_sel_hi:[0,1,1]
	v_cvt_pk_bf16_f32 v190, v186, v187
	ds_write_b32 v191, v190 offset:11712
	v_pk_fma_f32 v[184:185], v[82:83], v[186:187], v[146:147] op_sel:[1,1,0] op_sel_hi:[1,0,1] neg_lo:[1,0,0]
	v_pk_fma_f32 v[188:189], v[82:83], v[186:187], v[184:185] op_sel_hi:[0,1,1]
	v_cvt_pk_bf16_f32 v190, v188, v189
	ds_write_b32 v191, v190 offset:11440
	v_pk_fma_f32 v[184:185], v[82:83], v[188:189], v[148:149] op_sel:[1,1,0] op_sel_hi:[1,0,1] neg_lo:[1,0,0]
	v_pk_fma_f32 v[186:187], v[82:83], v[188:189], v[184:185] op_sel_hi:[0,1,1]
	v_cvt_pk_bf16_f32 v190, v186, v187
	ds_write_b32 v191, v190 offset:11168
	v_pk_fma_f32 v[184:185], v[82:83], v[186:187], v[150:151] op_sel:[1,1,0] op_sel_hi:[1,0,1] neg_lo:[1,0,0]
	v_pk_fma_f32 v[188:189], v[82:83], v[186:187], v[184:185] op_sel_hi:[0,1,1]
	v_cvt_pk_bf16_f32 v190, v188, v189
	ds_write_b32 v191, v190 offset:10896
	v_pk_fma_f32 v[184:185], v[82:83], v[188:189], v[152:153] op_sel:[1,1,0] op_sel_hi:[1,0,1] neg_lo:[1,0,0]
	v_pk_fma_f32 v[186:187], v[82:83], v[188:189], v[184:185] op_sel_hi:[0,1,1]
	v_cvt_pk_bf16_f32 v190, v186, v187
	ds_write_b32 v191, v190 offset:10624
	v_pk_fma_f32 v[184:185], v[82:83], v[186:187], v[154:155] op_sel:[1,1,0] op_sel_hi:[1,0,1] neg_lo:[1,0,0]
	v_pk_fma_f32 v[188:189], v[82:83], v[186:187], v[184:185] op_sel_hi:[0,1,1]
	v_cvt_pk_bf16_f32 v190, v188, v189
	ds_write_b32 v191, v190 offset:10352
	v_pk_fma_f32 v[184:185], v[82:83], v[188:189], v[156:157] op_sel:[1,1,0] op_sel_hi:[1,0,1] neg_lo:[1,0,0]
	v_pk_fma_f32 v[186:187], v[82:83], v[188:189], v[184:185] op_sel_hi:[0,1,1]
	v_cvt_pk_bf16_f32 v190, v186, v187
	ds_write_b32 v191, v190 offset:10080
	v_pk_fma_f32 v[184:185], v[82:83], v[186:187], v[158:159] op_sel:[1,1,0] op_sel_hi:[1,0,1] neg_lo:[1,0,0]
	v_pk_fma_f32 v[188:189], v[82:83], v[186:187], v[184:185] op_sel_hi:[0,1,1]
	v_cvt_pk_bf16_f32 v190, v188, v189
	ds_write_b32 v191, v190 offset:9808
	v_pk_fma_f32 v[184:185], v[82:83], v[188:189], v[160:161] op_sel:[1,1,0] op_sel_hi:[1,0,1] neg_lo:[1,0,0]
	v_pk_fma_f32 v[186:187], v[82:83], v[188:189], v[184:185] op_sel_hi:[0,1,1]
	v_cvt_pk_bf16_f32 v190, v186, v187
	ds_write_b32 v191, v190 offset:9536
	v_pk_fma_f32 v[184:185], v[82:83], v[186:187], v[162:163] op_sel:[1,1,0] op_sel_hi:[1,0,1] neg_lo:[1,0,0]
	v_pk_fma_f32 v[188:189], v[82:83], v[186:187], v[184:185] op_sel_hi:[0,1,1]
	v_cvt_pk_bf16_f32 v190, v188, v189
	ds_write_b32 v191, v190 offset:9264
	v_pk_fma_f32 v[184:185], v[82:83], v[188:189], v[164:165] op_sel:[1,1,0] op_sel_hi:[1,0,1] neg_lo:[1,0,0]
	v_pk_fma_f32 v[186:187], v[82:83], v[188:189], v[184:185] op_sel_hi:[0,1,1]
	v_cvt_pk_bf16_f32 v190, v186, v187
	ds_write_b32 v191, v190 offset:8992
	v_pk_fma_f32 v[184:185], v[82:83], v[186:187], v[166:167] op_sel:[1,1,0] op_sel_hi:[1,0,1] neg_lo:[1,0,0]
	v_pk_fma_f32 v[188:189], v[82:83], v[186:187], v[184:185] op_sel_hi:[0,1,1]
	v_cvt_pk_bf16_f32 v190, v188, v189
	ds_write_b32 v191, v190 offset:8720
	v_pk_fma_f32 v[184:185], v[82:83], v[188:189], v[168:169] op_sel:[1,1,0] op_sel_hi:[1,0,1] neg_lo:[1,0,0]
	v_pk_fma_f32 v[186:187], v[82:83], v[188:189], v[184:185] op_sel_hi:[0,1,1]
	v_mov_b32_e32 v103, v186
	v_mov_b32_e32 v108, v187
	v_cvt_pk_bf16_f32 v190, v186, v187
	ds_write_b32 v191, v190 offset:8448
	s_waitcnt vmcnt(0) lgkmcnt(0)
	ds_read_b128 v[76:79], v81 offset:8448
	ds_read_b128 v[104:107], v81 offset:8512
	s_waitcnt lgkmcnt(1)
	v_mfma_f32_16x16x32_bf16 v[76:79], v[76:79], v[32:35], 0
	s_waitcnt lgkmcnt(0)
	v_mfma_f32_16x16x32_bf16 v[76:79], v[104:107], v[28:31], v[76:79]
	ds_read_b128 v[104:107], v81 offset:8576
	s_waitcnt lgkmcnt(0)
	v_mfma_f32_16x16x32_bf16 v[76:79], v[104:107], v[24:27], v[76:79]
	ds_read_b128 v[104:107], v81 offset:8640
	ds_write2_b32 v88, v40, v36 offset1:16
	ds_write2_b32 v88, v41, v37 offset0:132 offset1:148
	ds_write2_b32 v89, v42, v38 offset0:8 offset1:24
	ds_write2_b32 v89, v43, v39 offset0:140 offset1:156
	v_mfma_f32_16x16x32_bf16 v[36:39], v[68:71], v[48:51], 0
	v_mfma_f32_16x16x32_bf16 v[40:43], v[68:71], v[44:47], 0
	s_nop 7
	ds_write2_b32 v88, v36, v40 offset0:32 offset1:48
	ds_write2_b32 v88, v37, v41 offset0:164 offset1:180
	ds_write2_b32 v89, v38, v42 offset0:40 offset1:56
	ds_write2_b32 v89, v39, v43 offset0:172 offset1:188
	v_mfma_f32_16x16x32_bf16 v[36:39], v[68:71], v[56:59], 0
	v_mfma_f32_16x16x32_bf16 v[40:43], v[68:71], v[52:55], 0
	s_nop 7
	ds_write2_b32 v88, v36, v40 offset0:64 offset1:80
	ds_write2_b32 v88, v37, v41 offset0:196 offset1:212
	ds_write2_b32 v89, v38, v42 offset0:72 offset1:88
	ds_write2_b32 v89, v39, v43 offset0:204 offset1:220
	v_mfma_f32_16x16x32_bf16 v[36:39], v[68:71], v[64:67], 0
	v_mfma_f32_16x16x32_bf16 v[40:43], v[68:71], v[60:63], 0
	s_nop 7
	ds_write2_b32 v88, v36, v40 offset0:96 offset1:112
	ds_write2_b32 v88, v37, v41 offset0:228 offset1:244
	ds_write2_b32 v89, v38, v42 offset0:104 offset1:120
	ds_write2_b32 v89, v39, v43 offset0:236 offset1:252
	s_waitcnt vmcnt(0) lgkmcnt(0)
	ds_read2st64_b32 v[36:37], v91 offset0:30 offset1:31
	ds_read2st64_b32 v[140:141], v84 offset0:28 offset1:29
	ds_read2st64_b32 v[142:143], v85 offset0:26 offset1:27
	ds_read2st64_b32 v[144:145], v92 offset0:24 offset1:25
	ds_read2st64_b32 v[146:147], v93 offset0:22 offset1:23
	ds_read2st64_b32 v[148:149], v94 offset0:20 offset1:21
	ds_read2st64_b32 v[150:151], v95 offset0:18 offset1:19
	ds_read2st64_b32 v[152:153], v96 offset0:16 offset1:17
	ds_read2st64_b32 v[154:155], v97 offset0:14 offset1:15
	ds_read2st64_b32 v[156:157], v98 offset0:12 offset1:13
	ds_read2st64_b32 v[158:159], v99 offset0:10 offset1:11
	ds_read2st64_b32 v[160:161], v100 offset0:8 offset1:9
	ds_read2st64_b32 v[162:163], v101 offset0:6 offset1:7
	ds_read2st64_b32 v[164:165], v102 offset0:4 offset1:5
	ds_read2_b32 v[166:167], v87 offset0:132 offset1:196
	ds_read2st64_b32 v[168:169], v87 offset1:1
	v_mov_b32_e32 v186, v103
	v_mov_b32_e32 v187, v108
	s_waitcnt lgkmcnt(0)
	v_mfma_f32_16x16x32_bf16 v[76:79], v[104:107], v[20:23], v[76:79]
	v_pk_fma_f32 v[184:185], v[82:83], v[186:187], v[36:37] op_sel:[1,1,0] op_sel_hi:[1,0,1] neg_lo:[1,0,0]
	v_pk_fma_f32 v[188:189], v[82:83], v[186:187], v[184:185] op_sel_hi:[0,1,1]
	v_cvt_pk_bf16_f32 v190, v188, v189
	v_and_b32_e32 v191, 63, v207
	v_lshl_add_u32 v191, v191, 1, v86
	ds_write_b32 v191, v190 offset:12528
	v_pk_fma_f32 v[184:185], v[82:83], v[188:189], v[140:141] op_sel:[1,1,0] op_sel_hi:[1,0,1] neg_lo:[1,0,0]
	v_pk_fma_f32 v[186:187], v[82:83], v[188:189], v[184:185] op_sel_hi:[0,1,1]
	v_cvt_pk_bf16_f32 v190, v186, v187
	ds_write_b32 v191, v190 offset:12256
	v_pk_fma_f32 v[184:185], v[82:83], v[186:187], v[142:143] op_sel:[1,1,0] op_sel_hi:[1,0,1] neg_lo:[1,0,0]
	v_pk_fma_f32 v[188:189], v[82:83], v[186:187], v[184:185] op_sel_hi:[0,1,1]
	v_cvt_pk_bf16_f32 v190, v188, v189
	ds_write_b32 v191, v190 offset:11984
	v_pk_fma_f32 v[184:185], v[82:83], v[188:189], v[144:145] op_sel:[1,1,0] op_sel_hi:[1,0,1] neg_lo:[1,0,0]
	v_pk_fma_f32 v[186:187], v[82:83], v[188:189], v[184:185] op_sel_hi:[0,1,1]
	v_cvt_pk_bf16_f32 v190, v186, v187
	ds_write_b32 v191, v190 offset:11712
	v_pk_fma_f32 v[184:185], v[82:83], v[186:187], v[146:147] op_sel:[1,1,0] op_sel_hi:[1,0,1] neg_lo:[1,0,0]
	v_pk_fma_f32 v[188:189], v[82:83], v[186:187], v[184:185] op_sel_hi:[0,1,1]
	v_cvt_pk_bf16_f32 v190, v188, v189
	ds_write_b32 v191, v190 offset:11440
	v_pk_fma_f32 v[184:185], v[82:83], v[188:189], v[148:149] op_sel:[1,1,0] op_sel_hi:[1,0,1] neg_lo:[1,0,0]
	v_pk_fma_f32 v[186:187], v[82:83], v[188:189], v[184:185] op_sel_hi:[0,1,1]
	v_cvt_pk_bf16_f32 v190, v186, v187
	ds_write_b32 v191, v190 offset:11168
	v_pk_fma_f32 v[184:185], v[82:83], v[186:187], v[150:151] op_sel:[1,1,0] op_sel_hi:[1,0,1] neg_lo:[1,0,0]
	v_pk_fma_f32 v[188:189], v[82:83], v[186:187], v[184:185] op_sel_hi:[0,1,1]
	v_cvt_pk_bf16_f32 v190, v188, v189
	ds_write_b32 v191, v190 offset:10896
	v_pk_fma_f32 v[184:185], v[82:83], v[188:189], v[152:153] op_sel:[1,1,0] op_sel_hi:[1,0,1] neg_lo:[1,0,0]
	v_pk_fma_f32 v[186:187], v[82:83], v[188:189], v[184:185] op_sel_hi:[0,1,1]
	v_cvt_pk_bf16_f32 v190, v186, v187
	ds_write_b32 v191, v190 offset:10624
	v_pk_fma_f32 v[184:185], v[82:83], v[186:187], v[154:155] op_sel:[1,1,0] op_sel_hi:[1,0,1] neg_lo:[1,0,0]
	v_pk_fma_f32 v[188:189], v[82:83], v[186:187], v[184:185] op_sel_hi:[0,1,1]
	v_cvt_pk_bf16_f32 v190, v188, v189
	ds_write_b32 v191, v190 offset:10352
	v_pk_fma_f32 v[184:185], v[82:83], v[188:189], v[156:157] op_sel:[1,1,0] op_sel_hi:[1,0,1] neg_lo:[1,0,0]
	v_pk_fma_f32 v[186:187], v[82:83], v[188:189], v[184:185] op_sel_hi:[0,1,1]
	v_cvt_pk_bf16_f32 v190, v186, v187
	ds_write_b32 v191, v190 offset:10080
	v_pk_fma_f32 v[184:185], v[82:83], v[186:187], v[158:159] op_sel:[1,1,0] op_sel_hi:[1,0,1] neg_lo:[1,0,0]
	v_pk_fma_f32 v[188:189], v[82:83], v[186:187], v[184:185] op_sel_hi:[0,1,1]
	v_cvt_pk_bf16_f32 v190, v188, v189
	ds_write_b32 v191, v190 offset:9808
	v_pk_fma_f32 v[184:185], v[82:83], v[188:189], v[160:161] op_sel:[1,1,0] op_sel_hi:[1,0,1] neg_lo:[1,0,0]
	v_pk_fma_f32 v[186:187], v[82:83], v[188:189], v[184:185] op_sel_hi:[0,1,1]
	v_cvt_pk_bf16_f32 v190, v186, v187
	ds_write_b32 v191, v190 offset:9536
	v_pk_fma_f32 v[184:185], v[82:83], v[186:187], v[162:163] op_sel:[1,1,0] op_sel_hi:[1,0,1] neg_lo:[1,0,0]
	v_pk_fma_f32 v[188:189], v[82:83], v[186:187], v[184:185] op_sel_hi:[0,1,1]
	v_cvt_pk_bf16_f32 v190, v188, v189
	ds_write_b32 v191, v190 offset:9264
	v_pk_fma_f32 v[184:185], v[82:83], v[188:189], v[164:165] op_sel:[1,1,0] op_sel_hi:[1,0,1] neg_lo:[1,0,0]
	v_pk_fma_f32 v[186:187], v[82:83], v[188:189], v[184:185] op_sel_hi:[0,1,1]
	v_cvt_pk_bf16_f32 v190, v186, v187
	ds_write_b32 v191, v190 offset:8992
	v_pk_fma_f32 v[184:185], v[82:83], v[186:187], v[166:167] op_sel:[1,1,0] op_sel_hi:[1,0,1] neg_lo:[1,0,0]
	v_pk_fma_f32 v[188:189], v[82:83], v[186:187], v[184:185] op_sel_hi:[0,1,1]
	v_cvt_pk_bf16_f32 v190, v188, v189
	ds_write_b32 v191, v190 offset:8720
	v_pk_fma_f32 v[184:185], v[82:83], v[188:189], v[168:169] op_sel:[1,1,0] op_sel_hi:[1,0,1] neg_lo:[1,0,0]
	v_pk_fma_f32 v[186:187], v[82:83], v[188:189], v[184:185] op_sel_hi:[0,1,1]
	v_mov_b32_e32 v36, v186
	v_mov_b32_e32 v37, v187
	v_cvt_pk_bf16_f32 v190, v186, v187
	ds_write_b32 v191, v190 offset:8448
	s_waitcnt vmcnt(0) lgkmcnt(0)
	ds_read_b128 v[36:39], v81 offset:8448
	s_waitcnt lgkmcnt(0)
	v_mfma_f32_16x16x32_bf16 v[32:35], v[36:39], v[32:35], 0
	ds_read_b128 v[36:39], v81 offset:8512
	s_waitcnt lgkmcnt(0)
	v_mfma_f32_16x16x32_bf16 v[28:31], v[36:39], v[28:31], v[32:35]
	s_nop 4
	ds_read_b128 v[32:35], v81 offset:8576
	s_waitcnt lgkmcnt(0)
	v_mfma_f32_16x16x32_bf16 v[24:27], v[32:35], v[24:27], v[28:31]
	s_nop 2
	ds_read_b128 v[28:31], v81 offset:8640
	s_waitcnt lgkmcnt(0)
	v_mfma_f32_16x16x32_bf16 v[20:23], v[28:31], v[20:23], v[24:27]
	s_nop 7
	v_pk_add_f32 v[24:25], v[0:1], v[20:21]
	v_and_or_b32 v0, v90, 15, v80
	v_add_u32_e32 v20, s6, v0
	v_ashrrev_i32_e32 v21, 31, v20
	v_lshrrev_b32_e32 v1, 2, v90
	v_lshl_add_u64 v[20:21], v[20:21], 2, s[76:77]
	v_and_b32_e32 v1, 12, v1
	global_load_dword v28, v[20:21], off
	v_add_u32_e32 v20, s8, v1
	v_ashrrev_i32_e32 v21, 31, v20
	v_ashrrev_i32_e32 v1, 31, v0
	v_lshlrev_b64 v[26:27], 9, v[20:21]
	v_lshl_add_u64 v[26:27], v[26:27], 0, v[0:1]
	v_lshl_add_u64 v[30:31], v[26:27], 1, s[36:37]
	global_load_ushort v29, v[30:31], off
	global_load_ushort v141, v[30:31], off offset:1024
	global_load_ushort v142, v[30:31], off offset:2048
	global_load_ushort v143, v[30:31], off offset:3072
	s_mov_b64 s[0:1], 0x4000
	v_lshl_add_u64 v[156:157], v[30:31], 0, s[0:1]
	global_load_ushort v144, v[156:157], off
	global_load_ushort v145, v[156:157], off offset:1024
	global_load_ushort v146, v[156:157], off offset:2048
	global_load_ushort v147, v[156:157], off offset:3072
	s_mov_b64 s[0:1], 0x8000
	v_lshl_add_u64 v[158:159], v[30:31], 0, s[0:1]
	global_load_ushort v148, v[158:159], off
	global_load_ushort v149, v[158:159], off offset:1024
	global_load_ushort v150, v[158:159], off offset:2048
	global_load_ushort v151, v[158:159], off offset:3072
	s_mov_b64 s[0:1], 0xc000
	v_lshl_add_u64 v[160:161], v[30:31], 0, s[0:1]
	global_load_ushort v152, v[160:161], off
	global_load_ushort v153, v[160:161], off offset:1024
	global_load_ushort v154, v[160:161], off offset:2048
	global_load_ushort v155, v[160:161], off offset:3072
	s_waitcnt vmcnt(0) lgkmcnt(0)
	v_lshlrev_b32_e32 v29, 16, v29
	v_fma_f32 v24, v28, v29, v24
	v_mul_f32_e32 v29, 0x3d372713, v24
	v_mul_f32_e32 v29, v24, v29
	v_fma_f32 v29, v24, v29, v24
	v_mul_f32_e32 v29, 0x3f4c422a, v29
	v_cmp_nlt_f32_e64 s[0:1], |v29|, s10
	s_and_saveexec_b64 s[2:3], s[0:1]
	s_xor_b64 s[0:1], exec, s[2:3]
	s_cbranch_execz .LBB0_1813
	v_add_f32_e64 v30, |v29|, |v29|
	v_mul_f32_e32 v31, 0x3fb8aa3b, v30
	v_rndne_f32_e32 v32, v31
	s_mov_b32 s2, 0x3fb8aa3b
	v_sub_f32_e32 v33, v31, v32
	v_fma_f32 v31, v30, s2, -v31
	v_fmac_f32_e32 v31, 0x32a5705f, v30
	v_add_f32_e32 v31, v33, v31
	v_cvt_i32_f32_e32 v32, v32
	v_exp_f32_e32 v31, v31
	s_mov_b32 s2, 0xc2ce8ed0
	v_cmp_ngt_f32_e32 vcc, s2, v30
	s_mov_b32 s2, 0x42b17218
	v_ldexp_f32 v31, v31, v32
	v_cndmask_b32_e32 v31, 0, v31, vcc
	v_cmp_nlt_f32_e32 vcc, s2, v30
	s_nop 1
	v_cndmask_b32_e32 v30, v235, v31, vcc
	v_add_f32_e32 v30, 1.0, v30
	v_rcp_f32_e32 v30, v30
	s_nop 0
	v_fma_f32 v30, v30, -2.0, 1.0
